# GEMM K-loops (all four): per-segment s_setprio flips replaced by one static s_setprio 1 for the trailing wave half (waves 4-7) before each unit's K-loop, s_setprio 0 after it
# speedup vs baseline: 1.0180x; 1.0137x over previous
.LBB0_52:
	s_ashr_i32 s43, s42, 31
	s_lshl_b64 s[16:17], s[42:43], 19
	s_add_u32 s44, s68, s16
	s_addc_u32 s45, s69, s17
	s_and_b64 s[16:17], s[40:41], exec
	s_cselect_b32 s15, s45, s51
	s_cselect_b32 s24, s44, s50
	s_ashr_i32 s13, s12, 31
	s_lshl_b64 s[16:17], s[12:13], 19
	s_add_u32 s46, s6, s16
	s_addc_u32 s47, s7, s17
	s_and_b64 s[16:17], s[40:41], exec
	s_cselect_b32 s13, s47, s53
	s_cselect_b32 s43, s46, s52
	s_add_u32 s50, s50, 0x40080
	s_addc_u32 s51, s51, 0
	s_add_u32 s49, s52, 0x100
	v_mov_b32_e32 v0, 0
	s_addc_u32 s67, s53, 0
	s_mov_b32 s70, -2
	s_waitcnt lgkmcnt(0)
	v_mov_b32_e32 v1, v0
	v_mov_b32_e32 v2, v0
	v_mov_b32_e32 v3, v0
	v_mov_b32_e32 v4, v0
	v_mov_b32_e32 v5, v0
	v_mov_b32_e32 v6, v0
	v_mov_b32_e32 v7, v0
	v_mov_b32_e32 v16, v0
	v_mov_b32_e32 v17, v0
	v_mov_b32_e32 v18, v0
	v_mov_b32_e32 v19, v0
	v_mov_b32_e32 v22, v0
	v_mov_b32_e32 v23, v0
	v_mov_b32_e32 v24, v0
	v_mov_b32_e32 v25, v0
	v_mov_b32_e32 v34, v0
	v_mov_b32_e32 v35, v0
	v_mov_b32_e32 v36, v0
	v_mov_b32_e32 v37, v0
	v_mov_b32_e32 v38, v0
	v_mov_b32_e32 v39, v0
	v_mov_b32_e32 v40, v0
	v_mov_b32_e32 v41, v0
	v_mov_b32_e32 v50, v0
	v_mov_b32_e32 v51, v0
	v_mov_b32_e32 v52, v0
	v_mov_b32_e32 v53, v0
	v_mov_b32_e32 v54, v0
	v_mov_b32_e32 v55, v0
	v_mov_b32_e32 v56, v0
	v_mov_b32_e32 v57, v0
	v_mov_b32_e32 v8, v0
	v_mov_b32_e32 v9, v0
	v_mov_b32_e32 v10, v0
	v_mov_b32_e32 v11, v0
	v_mov_b32_e32 v12, v0
	v_mov_b32_e32 v13, v0
	v_mov_b32_e32 v14, v0
	v_mov_b32_e32 v15, v0
	v_mov_b32_e32 v26, v0
	v_mov_b32_e32 v27, v0
	v_mov_b32_e32 v28, v0
	v_mov_b32_e32 v29, v0
	v_mov_b32_e32 v30, v0
	v_mov_b32_e32 v31, v0
	v_mov_b32_e32 v32, v0
	v_mov_b32_e32 v33, v0
	v_mov_b32_e32 v42, v0
	v_mov_b32_e32 v43, v0
	v_mov_b32_e32 v44, v0
	v_mov_b32_e32 v45, v0
	v_mov_b32_e32 v46, v0
	v_mov_b32_e32 v47, v0
	v_mov_b32_e32 v48, v0
	v_mov_b32_e32 v49, v0
	v_mov_b32_e32 v58, v0
	v_mov_b32_e32 v59, v0
	v_mov_b32_e32 v60, v0
	v_mov_b32_e32 v61, v0
	v_mov_b32_e32 v62, v0
	v_mov_b32_e32 v63, v0
	v_mov_b32_e32 v64, v0
	v_mov_b32_e32 v65, v0
	v_mov_b32_e32 v66, v0
	v_mov_b32_e32 v67, v0
	v_mov_b32_e32 v68, v0
	v_mov_b32_e32 v69, v0
	v_mov_b32_e32 v70, v0
	v_mov_b32_e32 v71, v0
	v_mov_b32_e32 v72, v0
	v_mov_b32_e32 v73, v0
	v_mov_b32_e32 v82, v0
	v_mov_b32_e32 v83, v0
	v_mov_b32_e32 v84, v0
	v_mov_b32_e32 v85, v0
	v_mov_b32_e32 v86, v0
	v_mov_b32_e32 v87, v0
	v_mov_b32_e32 v88, v0
	v_mov_b32_e32 v89, v0
	v_mov_b32_e32 v98, v0
	v_mov_b32_e32 v99, v0
	v_mov_b32_e32 v100, v0
	v_mov_b32_e32 v101, v0
	v_mov_b32_e32 v102, v0
	v_mov_b32_e32 v103, v0
	v_mov_b32_e32 v104, v0
	v_mov_b32_e32 v105, v0
	v_mov_b32_e32 v114, v0
	v_mov_b32_e32 v115, v0
	v_mov_b32_e32 v116, v0
	v_mov_b32_e32 v117, v0
	v_mov_b32_e32 v118, v0
	v_mov_b32_e32 v119, v0
	v_mov_b32_e32 v120, v0
	v_mov_b32_e32 v121, v0
	v_mov_b32_e32 v74, v0
	v_mov_b32_e32 v75, v0
	v_mov_b32_e32 v76, v0
	v_mov_b32_e32 v77, v0
	v_mov_b32_e32 v78, v0
	v_mov_b32_e32 v79, v0
	v_mov_b32_e32 v80, v0
	v_mov_b32_e32 v81, v0
	v_mov_b32_e32 v90, v0
	v_mov_b32_e32 v91, v0
	v_mov_b32_e32 v92, v0
	v_mov_b32_e32 v93, v0
	v_mov_b32_e32 v94, v0
	v_mov_b32_e32 v95, v0
	v_mov_b32_e32 v96, v0
	v_mov_b32_e32 v97, v0
	v_mov_b32_e32 v106, v0
	v_mov_b32_e32 v107, v0
	v_mov_b32_e32 v108, v0
	v_mov_b32_e32 v109, v0
	v_mov_b32_e32 v110, v0
	v_mov_b32_e32 v111, v0
	v_mov_b32_e32 v112, v0
	v_mov_b32_e32 v113, v0
	v_mov_b32_e32 v122, v0
	v_mov_b32_e32 v123, v0
	v_mov_b32_e32 v124, v0
	v_mov_b32_e32 v125, v0
	v_mov_b32_e32 v126, v0
	v_mov_b32_e32 v127, v0
	v_mov_b32_e32 v128, v0
	v_mov_b32_e32 v129, v0
	s_cmp_lg_u64 s[10:11], 0
	s_cbranch_scc1 .Lprio_skip_out
	s_setprio 1
.Lprio_skip_out:
.LBB0_53:
	s_add_u32 s16, s50, 0xfffc0080
	s_addc_u32 s17, s51, -1
	s_add_i32 s71, 0, 0x10000
	s_cmp_eq_u32 s70, 12
	s_cselect_b32 s55, s15, s17
	s_cselect_b32 s54, s24, s16
	v_add_u32_e32 v154, s71, v163
	s_cselect_b32 s53, s13, s67
	s_cselect_b32 s52, s43, s49
	s_add_i32 s75, 0, 0x14000
	ds_read_b128 v[144:147], v154
	ds_read_b128 v[168:171], v154 offset:1024
	ds_read_b128 v[172:175], v154 offset:2048
	ds_read_b128 v[176:179], v154 offset:3072
	v_add_u32_e32 v154, s75, v163
	ds_read_b128 v[180:183], v154
	ds_read_b128 v[184:187], v154 offset:1024
	ds_read_b128 v[208:211], v154 offset:2048
	ds_read_b128 v[212:215], v154 offset:3072
	v_lshl_add_u64 v[154:155], s[50:51], 0, v[140:141]
	s_add_i32 m0, s28, 0xc000
	ds_read_b128 v[216:219], v166
	ds_read_b128 v[220:223], v166 offset:1024
	ds_read_b128 v[224:227], v166 offset:2048
	ds_read_b128 v[228:231], v166 offset:3072
	ds_read_b128 v[232:235], v166 offset:4096
	ds_read_b128 v[236:239], v166 offset:5120
	ds_read_b128 v[240:243], v166 offset:6144
	ds_read_b128 v[244:247], v166 offset:7168
	global_load_lds_dwordx4 v[154:155], off
	v_lshl_add_u64 v[154:155], s[50:51], 0, v[142:143]
	s_add_i32 m0, s28, 0xe000
	s_nop 0
	global_load_lds_dwordx4 v[154:155], off
	s_waitcnt vmcnt(8)
	s_waitcnt lgkmcnt(0)
	s_barrier
	s_waitcnt lgkmcnt(0)
	v_mfma_f32_16x16x32_bf16 v[126:129], v[144:147], v[216:219], v[126:129]
	v_mfma_f32_16x16x32_bf16 v[122:125], v[172:175], v[216:219], v[122:125]
	v_mfma_f32_16x16x32_bf16 v[110:113], v[144:147], v[224:227], v[110:113]
	v_mfma_f32_16x16x32_bf16 v[106:109], v[172:175], v[224:227], v[106:109]
	v_mfma_f32_16x16x32_bf16 v[94:97], v[144:147], v[232:235], v[94:97]
	v_mfma_f32_16x16x32_bf16 v[90:93], v[172:175], v[232:235], v[90:93]
	v_mfma_f32_16x16x32_bf16 v[78:81], v[144:147], v[240:243], v[78:81]
	v_mfma_f32_16x16x32_bf16 v[74:77], v[172:175], v[240:243], v[74:77]
	v_mfma_f32_16x16x32_bf16 v[126:129], v[168:171], v[220:223], v[126:129]
	v_mfma_f32_16x16x32_bf16 v[122:125], v[176:179], v[220:223], v[122:125]
	v_mfma_f32_16x16x32_bf16 v[110:113], v[168:171], v[228:231], v[110:113]
	v_mfma_f32_16x16x32_bf16 v[106:109], v[176:179], v[228:231], v[106:109]
	v_mfma_f32_16x16x32_bf16 v[94:97], v[168:171], v[236:239], v[94:97]
	v_mfma_f32_16x16x32_bf16 v[90:93], v[176:179], v[236:239], v[90:93]
	v_mfma_f32_16x16x32_bf16 v[78:81], v[168:171], v[244:247], v[78:81]
	v_mfma_f32_16x16x32_bf16 v[74:77], v[176:179], v[244:247], v[74:77]
	v_mfma_f32_16x16x32_bf16 v[118:121], v[180:183], v[216:219], v[118:121]
	v_mfma_f32_16x16x32_bf16 v[114:117], v[208:211], v[216:219], v[114:117]
	v_mfma_f32_16x16x32_bf16 v[102:105], v[180:183], v[224:227], v[102:105]
	v_mfma_f32_16x16x32_bf16 v[98:101], v[208:211], v[224:227], v[98:101]
	v_mfma_f32_16x16x32_bf16 v[86:89], v[180:183], v[232:235], v[86:89]
	v_mfma_f32_16x16x32_bf16 v[82:85], v[208:211], v[232:235], v[82:85]
	v_mfma_f32_16x16x32_bf16 v[70:73], v[180:183], v[240:243], v[70:73]
	v_mfma_f32_16x16x32_bf16 v[66:69], v[208:211], v[240:243], v[66:69]
	v_mfma_f32_16x16x32_bf16 v[118:121], v[184:187], v[220:223], v[118:121]
	v_mfma_f32_16x16x32_bf16 v[114:117], v[212:215], v[220:223], v[114:117]
	v_mfma_f32_16x16x32_bf16 v[102:105], v[184:187], v[228:231], v[102:105]
	v_mfma_f32_16x16x32_bf16 v[98:101], v[212:215], v[228:231], v[98:101]
	v_mfma_f32_16x16x32_bf16 v[86:89], v[184:187], v[236:239], v[86:89]
	v_mfma_f32_16x16x32_bf16 v[82:85], v[212:215], v[236:239], v[82:85]
	v_mfma_f32_16x16x32_bf16 v[70:73], v[184:187], v[244:247], v[70:73]
	v_mfma_f32_16x16x32_bf16 v[66:69], v[212:215], v[244:247], v[66:69]
	s_barrier
	s_add_i32 s16, s71, s27
	v_lshl_add_u64 v[154:155], s[52:53], 0, v[132:133]
	s_mov_b32 m0, s16
	ds_read_b128 v[216:219], v166 offset:16384
	ds_read_b128 v[220:223], v166 offset:17408
	ds_read_b128 v[224:227], v166 offset:18432
	ds_read_b128 v[228:231], v166 offset:19456
	ds_read_b128 v[232:235], v166 offset:20480
	ds_read_b128 v[236:239], v166 offset:21504
	ds_read_b128 v[240:243], v166 offset:22528
	ds_read_b128 v[244:247], v166 offset:23552
	global_load_lds_dwordx4 v[154:155], off
	s_add_i32 m0, s16, 0x2000
	s_add_u32 s16, s52, 0x40000
	v_lshl_add_u64 v[156:157], s[52:53], 0, v[136:137]
	s_addc_u32 s17, s53, 0
	s_add_i32 s71, s75, s27
	global_load_lds_dwordx4 v[156:157], off
	v_lshl_add_u64 v[188:189], s[16:17], 0, v[132:133]
	s_mov_b32 m0, s71
	v_lshl_add_u64 v[248:249], s[54:55], 0, v[134:135]
	global_load_lds_dwordx4 v[188:189], off
	v_lshl_add_u64 v[188:189], s[16:17], 0, v[136:137]
	s_add_i32 m0, s71, 0x2000
	s_nop 0
	global_load_lds_dwordx4 v[188:189], off
	v_lshl_add_u64 v[188:189], s[54:55], 0, v[130:131]
	s_mov_b32 m0, s28
	s_nop 0
	global_load_lds_dwordx4 v[188:189], off
	s_mov_b32 m0, s29
	s_nop 0
	global_load_lds_dwordx4 v[248:249], off
	s_waitcnt vmcnt(8)
	s_waitcnt lgkmcnt(0)
	s_barrier
	s_waitcnt lgkmcnt(0)
	v_mfma_f32_16x16x32_bf16 v[62:65], v[144:147], v[216:219], v[62:65]
	v_mfma_f32_16x16x32_bf16 v[58:61], v[172:175], v[216:219], v[58:61]
	v_mfma_f32_16x16x32_bf16 v[46:49], v[144:147], v[224:227], v[46:49]
	v_mfma_f32_16x16x32_bf16 v[42:45], v[172:175], v[224:227], v[42:45]
	v_mfma_f32_16x16x32_bf16 v[30:33], v[144:147], v[232:235], v[30:33]
	v_mfma_f32_16x16x32_bf16 v[26:29], v[172:175], v[232:235], v[26:29]
	v_mfma_f32_16x16x32_bf16 v[12:15], v[144:147], v[240:243], v[12:15]
	v_mfma_f32_16x16x32_bf16 v[8:11], v[172:175], v[240:243], v[8:11]
	v_mfma_f32_16x16x32_bf16 v[62:65], v[168:171], v[220:223], v[62:65]
	v_mfma_f32_16x16x32_bf16 v[58:61], v[176:179], v[220:223], v[58:61]
	v_mfma_f32_16x16x32_bf16 v[46:49], v[168:171], v[228:231], v[46:49]
	v_mfma_f32_16x16x32_bf16 v[42:45], v[176:179], v[228:231], v[42:45]
	v_mfma_f32_16x16x32_bf16 v[30:33], v[168:171], v[236:239], v[30:33]
	v_mfma_f32_16x16x32_bf16 v[26:29], v[176:179], v[236:239], v[26:29]
	v_mfma_f32_16x16x32_bf16 v[12:15], v[168:171], v[244:247], v[12:15]
	v_mfma_f32_16x16x32_bf16 v[8:11], v[176:179], v[244:247], v[8:11]
	v_mfma_f32_16x16x32_bf16 v[54:57], v[180:183], v[216:219], v[54:57]
	v_mfma_f32_16x16x32_bf16 v[50:53], v[208:211], v[216:219], v[50:53]
	v_mfma_f32_16x16x32_bf16 v[38:41], v[180:183], v[224:227], v[38:41]
	v_mfma_f32_16x16x32_bf16 v[34:37], v[208:211], v[224:227], v[34:37]
	v_mfma_f32_16x16x32_bf16 v[22:25], v[180:183], v[232:235], v[22:25]
	v_mfma_f32_16x16x32_bf16 v[16:19], v[208:211], v[232:235], v[16:19]
	v_mfma_f32_16x16x32_bf16 v[4:7], v[180:183], v[240:243], v[4:7]
	v_mfma_f32_16x16x32_bf16 v[0:3], v[208:211], v[240:243], v[0:3]
	v_mfma_f32_16x16x32_bf16 v[54:57], v[184:187], v[220:223], v[54:57]
	v_mfma_f32_16x16x32_bf16 v[50:53], v[212:215], v[220:223], v[50:53]
	v_mfma_f32_16x16x32_bf16 v[38:41], v[184:187], v[228:231], v[38:41]
	v_mfma_f32_16x16x32_bf16 v[34:37], v[212:215], v[228:231], v[34:37]
	v_mfma_f32_16x16x32_bf16 v[22:25], v[184:187], v[236:239], v[22:25]
	v_mfma_f32_16x16x32_bf16 v[16:19], v[212:215], v[236:239], v[16:19]
	v_mfma_f32_16x16x32_bf16 v[4:7], v[184:187], v[244:247], v[4:7]
	v_mfma_f32_16x16x32_bf16 v[0:3], v[212:215], v[244:247], v[0:3]
	s_barrier
	s_add_i32 s71, 0, 0x18000
	v_add_u32_e32 v167, s71, v163
	s_add_i32 s75, 0, 0x1c000
	ds_read_b128 v[144:147], v167
	ds_read_b128 v[168:171], v167 offset:1024
	ds_read_b128 v[172:175], v167 offset:2048
	ds_read_b128 v[176:179], v167 offset:3072
	v_add_u32_e32 v167, s75, v163
	ds_read_b128 v[180:183], v167
	ds_read_b128 v[184:187], v167 offset:1024
	ds_read_b128 v[208:211], v167 offset:2048
	ds_read_b128 v[212:215], v167 offset:3072
	s_add_u32 s16, s54, 0x40000
	s_addc_u32 s17, s55, 0
	s_mov_b32 m0, s30
	v_lshl_add_u64 v[250:251], s[16:17], 0, v[130:131]
	ds_read_b128 v[216:219], v166 offset:32768
	ds_read_b128 v[220:223], v166 offset:33792
	ds_read_b128 v[224:227], v166 offset:34816
	ds_read_b128 v[228:231], v166 offset:35840
	ds_read_b128 v[232:235], v166 offset:36864
	ds_read_b128 v[236:239], v166 offset:37888
	ds_read_b128 v[240:243], v166 offset:38912
	ds_read_b128 v[244:247], v166 offset:39936
	global_load_lds_dwordx4 v[250:251], off
	v_lshl_add_u64 v[250:251], s[16:17], 0, v[134:135]
	s_mov_b32 m0, s33
	s_nop 0
	global_load_lds_dwordx4 v[250:251], off
	s_waitcnt vmcnt(8)
	s_waitcnt lgkmcnt(0)
	s_barrier
	s_waitcnt lgkmcnt(0)
	v_mfma_f32_16x16x32_bf16 v[126:129], v[144:147], v[216:219], v[126:129]
	v_mfma_f32_16x16x32_bf16 v[122:125], v[172:175], v[216:219], v[122:125]
	v_mfma_f32_16x16x32_bf16 v[110:113], v[144:147], v[224:227], v[110:113]
	v_mfma_f32_16x16x32_bf16 v[106:109], v[172:175], v[224:227], v[106:109]
	v_mfma_f32_16x16x32_bf16 v[94:97], v[144:147], v[232:235], v[94:97]
	v_mfma_f32_16x16x32_bf16 v[90:93], v[172:175], v[232:235], v[90:93]
	v_mfma_f32_16x16x32_bf16 v[78:81], v[144:147], v[240:243], v[78:81]
	v_mfma_f32_16x16x32_bf16 v[74:77], v[172:175], v[240:243], v[74:77]
	v_mfma_f32_16x16x32_bf16 v[126:129], v[168:171], v[220:223], v[126:129]
	v_mfma_f32_16x16x32_bf16 v[122:125], v[176:179], v[220:223], v[122:125]
	v_mfma_f32_16x16x32_bf16 v[110:113], v[168:171], v[228:231], v[110:113]
	v_mfma_f32_16x16x32_bf16 v[106:109], v[176:179], v[228:231], v[106:109]
	v_mfma_f32_16x16x32_bf16 v[94:97], v[168:171], v[236:239], v[94:97]
	v_mfma_f32_16x16x32_bf16 v[90:93], v[176:179], v[236:239], v[90:93]
	v_mfma_f32_16x16x32_bf16 v[78:81], v[168:171], v[244:247], v[78:81]
	v_mfma_f32_16x16x32_bf16 v[74:77], v[176:179], v[244:247], v[74:77]
	v_mfma_f32_16x16x32_bf16 v[118:121], v[180:183], v[216:219], v[118:121]
	v_mfma_f32_16x16x32_bf16 v[114:117], v[208:211], v[216:219], v[114:117]
	v_mfma_f32_16x16x32_bf16 v[102:105], v[180:183], v[224:227], v[102:105]
	v_mfma_f32_16x16x32_bf16 v[98:101], v[208:211], v[224:227], v[98:101]
	v_mfma_f32_16x16x32_bf16 v[86:89], v[180:183], v[232:235], v[86:89]
	v_mfma_f32_16x16x32_bf16 v[82:85], v[208:211], v[232:235], v[82:85]
	v_mfma_f32_16x16x32_bf16 v[70:73], v[180:183], v[240:243], v[70:73]
	v_mfma_f32_16x16x32_bf16 v[66:69], v[208:211], v[240:243], v[66:69]
	v_mfma_f32_16x16x32_bf16 v[118:121], v[184:187], v[220:223], v[118:121]
	v_mfma_f32_16x16x32_bf16 v[114:117], v[212:215], v[220:223], v[114:117]
	v_mfma_f32_16x16x32_bf16 v[102:105], v[184:187], v[228:231], v[102:105]
	v_mfma_f32_16x16x32_bf16 v[98:101], v[212:215], v[228:231], v[98:101]
	v_mfma_f32_16x16x32_bf16 v[86:89], v[184:187], v[236:239], v[86:89]
	v_mfma_f32_16x16x32_bf16 v[82:85], v[212:215], v[236:239], v[82:85]
	v_mfma_f32_16x16x32_bf16 v[70:73], v[184:187], v[244:247], v[70:73]
	v_mfma_f32_16x16x32_bf16 v[66:69], v[212:215], v[244:247], v[66:69]
	s_barrier
	s_add_i32 s16, s71, s27
	v_lshl_add_u64 v[154:155], v[154:155], 0, s[34:35]
	s_mov_b32 m0, s16
	ds_read_b128 v[216:219], v166 offset:49152
	ds_read_b128 v[220:223], v166 offset:50176
	ds_read_b128 v[224:227], v166 offset:51200
	ds_read_b128 v[228:231], v166 offset:52224
	ds_read_b128 v[232:235], v166 offset:53248
	ds_read_b128 v[236:239], v166 offset:54272
	ds_read_b128 v[240:243], v166 offset:55296
	ds_read_b128 v[244:247], v166 offset:56320
	global_load_lds_dwordx4 v[154:155], off
	s_add_i32 m0, s16, 0x2000
	s_add_u32 s16, s52, 0x40080
	v_lshl_add_u64 v[154:155], v[156:157], 0, s[34:35]
	s_addc_u32 s17, s53, 0
	s_add_i32 s52, s75, s27
	global_load_lds_dwordx4 v[154:155], off
	v_lshl_add_u64 v[154:155], s[16:17], 0, v[132:133]
	s_mov_b32 m0, s52
	s_nop 0
	global_load_lds_dwordx4 v[154:155], off
	v_lshl_add_u64 v[154:155], s[16:17], 0, v[136:137]
	s_add_i32 m0, s52, 0x2000
	s_nop 0
	global_load_lds_dwordx4 v[154:155], off
	v_lshl_add_u64 v[154:155], v[188:189], 0, s[34:35]
	s_mov_b32 m0, s57
	s_nop 0
	global_load_lds_dwordx4 v[154:155], off
	v_lshl_add_u64 v[154:155], v[248:249], 0, s[34:35]
	s_mov_b32 m0, s58
	s_nop 0
	global_load_lds_dwordx4 v[154:155], off
	s_waitcnt vmcnt(8)
	s_waitcnt lgkmcnt(0)
	s_barrier
	s_waitcnt lgkmcnt(0)
	v_mfma_f32_16x16x32_bf16 v[62:65], v[144:147], v[216:219], v[62:65]
	v_mfma_f32_16x16x32_bf16 v[58:61], v[172:175], v[216:219], v[58:61]
	v_mfma_f32_16x16x32_bf16 v[46:49], v[144:147], v[224:227], v[46:49]
	v_mfma_f32_16x16x32_bf16 v[42:45], v[172:175], v[224:227], v[42:45]
	v_mfma_f32_16x16x32_bf16 v[30:33], v[144:147], v[232:235], v[30:33]
	v_mfma_f32_16x16x32_bf16 v[26:29], v[172:175], v[232:235], v[26:29]
	v_mfma_f32_16x16x32_bf16 v[12:15], v[144:147], v[240:243], v[12:15]
	v_mfma_f32_16x16x32_bf16 v[8:11], v[172:175], v[240:243], v[8:11]
	v_mfma_f32_16x16x32_bf16 v[62:65], v[168:171], v[220:223], v[62:65]
	v_mfma_f32_16x16x32_bf16 v[58:61], v[176:179], v[220:223], v[58:61]
	v_mfma_f32_16x16x32_bf16 v[46:49], v[168:171], v[228:231], v[46:49]
	v_mfma_f32_16x16x32_bf16 v[42:45], v[176:179], v[228:231], v[42:45]
	v_mfma_f32_16x16x32_bf16 v[30:33], v[168:171], v[236:239], v[30:33]
	v_mfma_f32_16x16x32_bf16 v[26:29], v[176:179], v[236:239], v[26:29]
	v_mfma_f32_16x16x32_bf16 v[12:15], v[168:171], v[244:247], v[12:15]
	v_mfma_f32_16x16x32_bf16 v[8:11], v[176:179], v[244:247], v[8:11]
	v_mfma_f32_16x16x32_bf16 v[54:57], v[180:183], v[216:219], v[54:57]
	v_mfma_f32_16x16x32_bf16 v[50:53], v[208:211], v[216:219], v[50:53]
	v_mfma_f32_16x16x32_bf16 v[38:41], v[180:183], v[224:227], v[38:41]
	v_mfma_f32_16x16x32_bf16 v[34:37], v[208:211], v[224:227], v[34:37]
	v_mfma_f32_16x16x32_bf16 v[22:25], v[180:183], v[232:235], v[22:25]
	v_mfma_f32_16x16x32_bf16 v[16:19], v[208:211], v[232:235], v[16:19]
	v_mfma_f32_16x16x32_bf16 v[4:7], v[180:183], v[240:243], v[4:7]
	v_mfma_f32_16x16x32_bf16 v[0:3], v[208:211], v[240:243], v[0:3]
	v_mfma_f32_16x16x32_bf16 v[54:57], v[184:187], v[220:223], v[54:57]
	v_mfma_f32_16x16x32_bf16 v[50:53], v[212:215], v[220:223], v[50:53]
	v_mfma_f32_16x16x32_bf16 v[38:41], v[184:187], v[228:231], v[38:41]
	v_mfma_f32_16x16x32_bf16 v[34:37], v[212:215], v[228:231], v[34:37]
	v_mfma_f32_16x16x32_bf16 v[22:25], v[184:187], v[236:239], v[22:25]
	v_mfma_f32_16x16x32_bf16 v[16:19], v[212:215], v[236:239], v[16:19]
	v_mfma_f32_16x16x32_bf16 v[4:7], v[184:187], v[244:247], v[4:7]
	v_mfma_f32_16x16x32_bf16 v[0:3], v[212:215], v[244:247], v[0:3]
	s_barrier
	s_add_i32 s70, s70, 2
	s_add_u32 s50, s50, 0x100
	s_addc_u32 s51, s51, 0
	s_add_u32 s49, s49, 0x100
	s_addc_u32 s67, s67, 0
	s_cmp_gt_u32 s70, 13
	s_cbranch_scc0 .LBB0_53
	s_setprio 0
	s_and_b64 vcc, exec, s[10:11]
	s_cbranch_vccz .LBB0_56
	s_barrier

.LBB0_1037:
	s_ashr_i32 s61, s60, 31
	s_lshl_b64 s[10:11], s[60:61], 19
	s_add_u32 s70, s18, s10
	s_addc_u32 s71, s19, s11
	s_and_b64 s[10:11], s[40:41], exec
	s_cselect_b32 s12, s71, s7
	s_cselect_b32 s13, s70, s6
	s_ashr_i32 s57, s56, 31
	s_lshl_b64 s[10:11], s[56:57], 19
	s_add_u32 s80, s58, s10
	s_addc_u32 s81, s59, s11
	s_and_b64 s[10:11], s[40:41], exec
	s_cselect_b32 s42, s81, s9
	s_cselect_b32 s43, s80, s8
	s_add_u32 s6, s6, 0x40080
	s_addc_u32 s7, s7, 0
	s_add_u32 s44, s8, 0x100
	v_mov_b32_e32 v0, 0
	s_addc_u32 s45, s9, 0
	s_mov_b32 s46, -2
	v_mov_b32_e32 v1, v0
	v_mov_b32_e32 v2, v0
	v_mov_b32_e32 v3, v0
	v_mov_b32_e32 v4, v0
	v_mov_b32_e32 v5, v0
	v_mov_b32_e32 v6, v0
	v_mov_b32_e32 v7, v0
	v_mov_b32_e32 v16, v0
	v_mov_b32_e32 v17, v0
	v_mov_b32_e32 v18, v0
	v_mov_b32_e32 v19, v0
	v_mov_b32_e32 v22, v0
	v_mov_b32_e32 v23, v0
	v_mov_b32_e32 v24, v0
	v_mov_b32_e32 v25, v0
	v_mov_b32_e32 v34, v0
	v_mov_b32_e32 v35, v0
	v_mov_b32_e32 v36, v0
	v_mov_b32_e32 v37, v0
	v_mov_b32_e32 v38, v0
	v_mov_b32_e32 v39, v0
	v_mov_b32_e32 v40, v0
	v_mov_b32_e32 v41, v0
	v_mov_b32_e32 v50, v0
	v_mov_b32_e32 v51, v0
	v_mov_b32_e32 v52, v0
	v_mov_b32_e32 v53, v0
	v_mov_b32_e32 v54, v0
	v_mov_b32_e32 v55, v0
	v_mov_b32_e32 v56, v0
	v_mov_b32_e32 v57, v0
	v_mov_b32_e32 v8, v0
	v_mov_b32_e32 v9, v0
	v_mov_b32_e32 v10, v0
	v_mov_b32_e32 v11, v0
	v_mov_b32_e32 v12, v0
	v_mov_b32_e32 v13, v0
	v_mov_b32_e32 v14, v0
	v_mov_b32_e32 v15, v0
	v_mov_b32_e32 v26, v0
	v_mov_b32_e32 v27, v0
	v_mov_b32_e32 v28, v0
	v_mov_b32_e32 v29, v0
	v_mov_b32_e32 v30, v0
	v_mov_b32_e32 v31, v0
	v_mov_b32_e32 v32, v0
	v_mov_b32_e32 v33, v0
	v_mov_b32_e32 v42, v0
	v_mov_b32_e32 v43, v0
	v_mov_b32_e32 v44, v0
	v_mov_b32_e32 v45, v0
	v_mov_b32_e32 v46, v0
	v_mov_b32_e32 v47, v0
	v_mov_b32_e32 v48, v0
	v_mov_b32_e32 v49, v0
	v_mov_b32_e32 v58, v0
	v_mov_b32_e32 v59, v0
	v_mov_b32_e32 v60, v0
	v_mov_b32_e32 v61, v0
	v_mov_b32_e32 v62, v0
	v_mov_b32_e32 v63, v0
	v_mov_b32_e32 v64, v0
	v_mov_b32_e32 v65, v0
	v_mov_b32_e32 v66, v0
	v_mov_b32_e32 v67, v0
	v_mov_b32_e32 v68, v0
	v_mov_b32_e32 v69, v0
	v_mov_b32_e32 v70, v0
	v_mov_b32_e32 v71, v0
	v_mov_b32_e32 v72, v0
	v_mov_b32_e32 v73, v0
	v_mov_b32_e32 v82, v0
	v_mov_b32_e32 v83, v0
	v_mov_b32_e32 v84, v0
	v_mov_b32_e32 v85, v0
	v_mov_b32_e32 v86, v0
	v_mov_b32_e32 v87, v0
	v_mov_b32_e32 v88, v0
	v_mov_b32_e32 v89, v0
	v_mov_b32_e32 v98, v0
	v_mov_b32_e32 v99, v0
	v_mov_b32_e32 v100, v0
	v_mov_b32_e32 v101, v0
	v_mov_b32_e32 v102, v0
	v_mov_b32_e32 v103, v0
	v_mov_b32_e32 v104, v0
	v_mov_b32_e32 v105, v0
	v_mov_b32_e32 v114, v0
	v_mov_b32_e32 v115, v0
	v_mov_b32_e32 v116, v0
	v_mov_b32_e32 v117, v0
	v_mov_b32_e32 v118, v0
	v_mov_b32_e32 v119, v0
	v_mov_b32_e32 v120, v0
	v_mov_b32_e32 v121, v0
	v_mov_b32_e32 v74, v0
	v_mov_b32_e32 v75, v0
	v_mov_b32_e32 v76, v0
	v_mov_b32_e32 v77, v0
	v_mov_b32_e32 v78, v0
	v_mov_b32_e32 v79, v0
	v_mov_b32_e32 v80, v0
	v_mov_b32_e32 v81, v0
	v_mov_b32_e32 v90, v0
	v_mov_b32_e32 v91, v0
	v_mov_b32_e32 v92, v0
	v_mov_b32_e32 v93, v0
	v_mov_b32_e32 v94, v0
	v_mov_b32_e32 v95, v0
	v_mov_b32_e32 v96, v0
	v_mov_b32_e32 v97, v0
	v_mov_b32_e32 v106, v0
	v_mov_b32_e32 v107, v0
	v_mov_b32_e32 v108, v0
	v_mov_b32_e32 v109, v0
	v_mov_b32_e32 v110, v0
	v_mov_b32_e32 v111, v0
	v_mov_b32_e32 v112, v0
	v_mov_b32_e32 v113, v0
	v_mov_b32_e32 v122, v0
	v_mov_b32_e32 v123, v0
	v_mov_b32_e32 v124, v0
	v_mov_b32_e32 v125, v0
	v_mov_b32_e32 v126, v0
	v_mov_b32_e32 v127, v0
	v_mov_b32_e32 v128, v0
	v_mov_b32_e32 v129, v0
	s_cmp_lg_u64 s[54:55], 0
	s_cbranch_scc1 .Lprio_skip_proj
	s_setprio 1
.Lprio_skip_proj:
.LBB0_1038:
	s_add_u32 s8, s6, 0xfffc0080
	s_addc_u32 s9, s7, -1
	s_add_i32 s16, 0, 0x10000
	s_cmp_eq_u32 s46, 12
	s_cselect_b32 s11, s12, s9
	s_cselect_b32 s10, s13, s8
	s_cselect_b32 s9, s42, s45
	s_cselect_b32 s8, s43, s44
	s_add_i32 s47, 0, 0x14000
	v_add_u32_e32 v142, s16, v207
	v_add_u32_e32 v154, s47, v207
	ds_read_b128 v[130:133], v142
	ds_read_b128 v[134:137], v142 offset:1024
	s_waitcnt lgkmcnt(0)
	ds_read_b128 v[138:141], v142 offset:2048
	ds_read_b128 v[142:145], v142 offset:3072
	ds_read_b128 v[176:179], v154
	ds_read_b128 v[180:183], v154 offset:1024
	ds_read_b128 v[184:187], v154 offset:2048
	ds_read_b128 v[214:217], v154 offset:3072
	v_lshl_add_u64 v[156:157], s[6:7], 0, v[172:173]
	s_add_i32 m0, s67, 0xc000
	ds_read_b128 v[218:221], v213
	ds_read_b128 v[222:225], v213 offset:1024
	ds_read_b128 v[226:229], v213 offset:2048
	ds_read_b128 v[230:233], v213 offset:3072
	ds_read_b128 v[234:237], v213 offset:4096
	ds_read_b128 v[238:241], v213 offset:5120
	ds_read_b128 v[242:245], v213 offset:6144
	ds_read_b128 v[246:249], v213 offset:7168
	global_load_lds_dwordx4 v[156:157], off
	v_lshl_add_u64 v[156:157], s[6:7], 0, v[174:175]
	s_add_i32 m0, s67, 0xe000
	s_nop 0
	global_load_lds_dwordx4 v[156:157], off
	s_waitcnt vmcnt(8)
	s_waitcnt lgkmcnt(0)
	s_barrier
	s_waitcnt lgkmcnt(0)
	v_mfma_f32_16x16x32_bf16 v[126:129], v[130:133], v[218:221], v[126:129]
	v_mfma_f32_16x16x32_bf16 v[122:125], v[138:141], v[218:221], v[122:125]
	v_mfma_f32_16x16x32_bf16 v[110:113], v[130:133], v[226:229], v[110:113]
	v_mfma_f32_16x16x32_bf16 v[106:109], v[138:141], v[226:229], v[106:109]
	v_mfma_f32_16x16x32_bf16 v[94:97], v[130:133], v[234:237], v[94:97]
	v_mfma_f32_16x16x32_bf16 v[90:93], v[138:141], v[234:237], v[90:93]
	v_mfma_f32_16x16x32_bf16 v[78:81], v[130:133], v[242:245], v[78:81]
	v_mfma_f32_16x16x32_bf16 v[74:77], v[138:141], v[242:245], v[74:77]
	v_mfma_f32_16x16x32_bf16 v[126:129], v[134:137], v[222:225], v[126:129]
	v_mfma_f32_16x16x32_bf16 v[122:125], v[142:145], v[222:225], v[122:125]
	v_mfma_f32_16x16x32_bf16 v[110:113], v[134:137], v[230:233], v[110:113]
	v_mfma_f32_16x16x32_bf16 v[106:109], v[142:145], v[230:233], v[106:109]
	v_mfma_f32_16x16x32_bf16 v[94:97], v[134:137], v[238:241], v[94:97]
	v_mfma_f32_16x16x32_bf16 v[90:93], v[142:145], v[238:241], v[90:93]
	v_mfma_f32_16x16x32_bf16 v[78:81], v[134:137], v[246:249], v[78:81]
	v_mfma_f32_16x16x32_bf16 v[74:77], v[142:145], v[246:249], v[74:77]
	v_mfma_f32_16x16x32_bf16 v[118:121], v[176:179], v[218:221], v[118:121]
	v_mfma_f32_16x16x32_bf16 v[114:117], v[184:187], v[218:221], v[114:117]
	v_mfma_f32_16x16x32_bf16 v[102:105], v[176:179], v[226:229], v[102:105]
	v_mfma_f32_16x16x32_bf16 v[98:101], v[184:187], v[226:229], v[98:101]
	v_mfma_f32_16x16x32_bf16 v[86:89], v[176:179], v[234:237], v[86:89]
	v_mfma_f32_16x16x32_bf16 v[82:85], v[184:187], v[234:237], v[82:85]
	v_mfma_f32_16x16x32_bf16 v[70:73], v[176:179], v[242:245], v[70:73]
	v_mfma_f32_16x16x32_bf16 v[66:69], v[184:187], v[242:245], v[66:69]
	v_mfma_f32_16x16x32_bf16 v[118:121], v[180:183], v[222:225], v[118:121]
	v_mfma_f32_16x16x32_bf16 v[114:117], v[214:217], v[222:225], v[114:117]
	v_mfma_f32_16x16x32_bf16 v[102:105], v[180:183], v[230:233], v[102:105]
	v_mfma_f32_16x16x32_bf16 v[98:101], v[214:217], v[230:233], v[98:101]
	v_mfma_f32_16x16x32_bf16 v[86:89], v[180:183], v[238:241], v[86:89]
	v_mfma_f32_16x16x32_bf16 v[82:85], v[214:217], v[238:241], v[82:85]
	v_mfma_f32_16x16x32_bf16 v[70:73], v[180:183], v[246:249], v[70:73]
	v_mfma_f32_16x16x32_bf16 v[66:69], v[214:217], v[246:249], v[66:69]
	s_barrier
	s_add_i32 s16, s16, s15
	v_lshl_add_u64 v[156:157], s[8:9], 0, v[148:149]
	s_mov_b32 m0, s16
	ds_read_b128 v[218:221], v213 offset:16384
	ds_read_b128 v[222:225], v213 offset:17408
	ds_read_b128 v[226:229], v213 offset:18432
	ds_read_b128 v[230:233], v213 offset:19456
	ds_read_b128 v[234:237], v213 offset:20480
	ds_read_b128 v[238:241], v213 offset:21504
	ds_read_b128 v[242:245], v213 offset:22528
	ds_read_b128 v[246:249], v213 offset:23552
	global_load_lds_dwordx4 v[156:157], off
	s_add_i32 m0, s16, 0x2000
	s_add_u32 s16, s8, 0x40000
	v_lshl_add_u64 v[188:189], s[8:9], 0, v[164:165]
	s_addc_u32 s17, s9, 0
	s_add_i32 s47, s47, s15
	global_load_lds_dwordx4 v[188:189], off
	v_lshl_add_u64 v[250:251], s[16:17], 0, v[148:149]
	s_mov_b32 m0, s47
	v_lshl_add_u64 v[252:253], s[10:11], 0, v[162:163]
	global_load_lds_dwordx4 v[250:251], off
	v_lshl_add_u64 v[250:251], s[16:17], 0, v[164:165]
	s_add_i32 m0, s47, 0x2000
	s_nop 0
	global_load_lds_dwordx4 v[250:251], off
	v_lshl_add_u64 v[250:251], s[10:11], 0, v[146:147]
	s_mov_b32 m0, s67
	s_nop 0
	global_load_lds_dwordx4 v[250:251], off
	s_mov_b32 m0, s82
	s_nop 0
	global_load_lds_dwordx4 v[252:253], off
	s_waitcnt vmcnt(8)
	s_waitcnt lgkmcnt(0)
	s_barrier
	s_waitcnt lgkmcnt(0)
	v_mfma_f32_16x16x32_bf16 v[62:65], v[130:133], v[218:221], v[62:65]
	v_mfma_f32_16x16x32_bf16 v[58:61], v[138:141], v[218:221], v[58:61]
	v_mfma_f32_16x16x32_bf16 v[46:49], v[130:133], v[226:229], v[46:49]
	v_mfma_f32_16x16x32_bf16 v[42:45], v[138:141], v[226:229], v[42:45]
	v_mfma_f32_16x16x32_bf16 v[30:33], v[130:133], v[234:237], v[30:33]
	v_mfma_f32_16x16x32_bf16 v[26:29], v[138:141], v[234:237], v[26:29]
	v_mfma_f32_16x16x32_bf16 v[12:15], v[130:133], v[242:245], v[12:15]
	v_mfma_f32_16x16x32_bf16 v[8:11], v[138:141], v[242:245], v[8:11]
	v_mfma_f32_16x16x32_bf16 v[62:65], v[134:137], v[222:225], v[62:65]
	v_mfma_f32_16x16x32_bf16 v[58:61], v[142:145], v[222:225], v[58:61]
	v_mfma_f32_16x16x32_bf16 v[46:49], v[134:137], v[230:233], v[46:49]
	v_mfma_f32_16x16x32_bf16 v[42:45], v[142:145], v[230:233], v[42:45]
	v_mfma_f32_16x16x32_bf16 v[30:33], v[134:137], v[238:241], v[30:33]
	v_mfma_f32_16x16x32_bf16 v[26:29], v[142:145], v[238:241], v[26:29]
	v_mfma_f32_16x16x32_bf16 v[12:15], v[134:137], v[246:249], v[12:15]
	v_mfma_f32_16x16x32_bf16 v[8:11], v[142:145], v[246:249], v[8:11]
	v_mfma_f32_16x16x32_bf16 v[54:57], v[176:179], v[218:221], v[54:57]
	v_mfma_f32_16x16x32_bf16 v[50:53], v[184:187], v[218:221], v[50:53]
	v_mfma_f32_16x16x32_bf16 v[38:41], v[176:179], v[226:229], v[38:41]
	v_mfma_f32_16x16x32_bf16 v[34:37], v[184:187], v[226:229], v[34:37]
	v_mfma_f32_16x16x32_bf16 v[22:25], v[176:179], v[234:237], v[22:25]
	v_mfma_f32_16x16x32_bf16 v[16:19], v[184:187], v[234:237], v[16:19]
	v_mfma_f32_16x16x32_bf16 v[4:7], v[176:179], v[242:245], v[4:7]
	v_mfma_f32_16x16x32_bf16 v[0:3], v[184:187], v[242:245], v[0:3]
	v_mfma_f32_16x16x32_bf16 v[54:57], v[180:183], v[222:225], v[54:57]
	v_mfma_f32_16x16x32_bf16 v[50:53], v[214:217], v[222:225], v[50:53]
	v_mfma_f32_16x16x32_bf16 v[38:41], v[180:183], v[230:233], v[38:41]
	v_mfma_f32_16x16x32_bf16 v[34:37], v[214:217], v[230:233], v[34:37]
	v_mfma_f32_16x16x32_bf16 v[22:25], v[180:183], v[238:241], v[22:25]
	v_mfma_f32_16x16x32_bf16 v[16:19], v[214:217], v[238:241], v[16:19]
	v_mfma_f32_16x16x32_bf16 v[4:7], v[180:183], v[246:249], v[4:7]
	v_mfma_f32_16x16x32_bf16 v[0:3], v[214:217], v[246:249], v[0:3]
	s_barrier
	s_add_i32 s16, 0, 0x18000
	s_add_i32 s17, 0, 0x1c000
	v_add_u32_e32 v142, s16, v207
	v_add_u32_e32 v154, s17, v207
	ds_read_b128 v[130:133], v142
	ds_read_b128 v[134:137], v142 offset:1024
	ds_read_b128 v[138:141], v142 offset:2048
	ds_read_b128 v[142:145], v142 offset:3072
	ds_read_b128 v[176:179], v154
	ds_read_b128 v[180:183], v154 offset:1024
	ds_read_b128 v[184:187], v154 offset:2048
	ds_read_b128 v[214:217], v154 offset:3072
	s_add_u32 s10, s10, 0x40000
	s_addc_u32 s11, s11, 0
	s_mov_b32 m0, s83
	v_lshl_add_u64 v[154:155], s[10:11], 0, v[146:147]
	ds_read_b128 v[218:221], v213 offset:32768
	ds_read_b128 v[222:225], v213 offset:33792
	ds_read_b128 v[226:229], v213 offset:34816
	ds_read_b128 v[230:233], v213 offset:35840
	ds_read_b128 v[234:237], v213 offset:36864
	ds_read_b128 v[238:241], v213 offset:37888
	ds_read_b128 v[242:245], v213 offset:38912
	ds_read_b128 v[246:249], v213 offset:39936
	global_load_lds_dwordx4 v[154:155], off
	v_lshl_add_u64 v[154:155], s[10:11], 0, v[162:163]
	s_mov_b32 m0, s84
	s_nop 0
	global_load_lds_dwordx4 v[154:155], off
	s_waitcnt vmcnt(8)
	s_waitcnt lgkmcnt(0)
	s_barrier
	s_waitcnt lgkmcnt(0)
	v_mfma_f32_16x16x32_bf16 v[126:129], v[130:133], v[218:221], v[126:129]
	v_mfma_f32_16x16x32_bf16 v[122:125], v[138:141], v[218:221], v[122:125]
	v_mfma_f32_16x16x32_bf16 v[110:113], v[130:133], v[226:229], v[110:113]
	v_mfma_f32_16x16x32_bf16 v[106:109], v[138:141], v[226:229], v[106:109]
	v_mfma_f32_16x16x32_bf16 v[94:97], v[130:133], v[234:237], v[94:97]
	v_mfma_f32_16x16x32_bf16 v[90:93], v[138:141], v[234:237], v[90:93]
	v_mfma_f32_16x16x32_bf16 v[78:81], v[130:133], v[242:245], v[78:81]
	v_mfma_f32_16x16x32_bf16 v[74:77], v[138:141], v[242:245], v[74:77]
	v_mfma_f32_16x16x32_bf16 v[126:129], v[134:137], v[222:225], v[126:129]
	v_mfma_f32_16x16x32_bf16 v[122:125], v[142:145], v[222:225], v[122:125]
	v_mfma_f32_16x16x32_bf16 v[110:113], v[134:137], v[230:233], v[110:113]
	v_mfma_f32_16x16x32_bf16 v[106:109], v[142:145], v[230:233], v[106:109]
	v_mfma_f32_16x16x32_bf16 v[94:97], v[134:137], v[238:241], v[94:97]
	v_mfma_f32_16x16x32_bf16 v[90:93], v[142:145], v[238:241], v[90:93]
	v_mfma_f32_16x16x32_bf16 v[78:81], v[134:137], v[246:249], v[78:81]
	v_mfma_f32_16x16x32_bf16 v[74:77], v[142:145], v[246:249], v[74:77]
	v_mfma_f32_16x16x32_bf16 v[118:121], v[176:179], v[218:221], v[118:121]
	v_mfma_f32_16x16x32_bf16 v[114:117], v[184:187], v[218:221], v[114:117]
	v_mfma_f32_16x16x32_bf16 v[102:105], v[176:179], v[226:229], v[102:105]
	v_mfma_f32_16x16x32_bf16 v[98:101], v[184:187], v[226:229], v[98:101]
	v_mfma_f32_16x16x32_bf16 v[86:89], v[176:179], v[234:237], v[86:89]
	v_mfma_f32_16x16x32_bf16 v[82:85], v[184:187], v[234:237], v[82:85]
	v_mfma_f32_16x16x32_bf16 v[70:73], v[176:179], v[242:245], v[70:73]
	v_mfma_f32_16x16x32_bf16 v[66:69], v[184:187], v[242:245], v[66:69]
	v_mfma_f32_16x16x32_bf16 v[118:121], v[180:183], v[222:225], v[118:121]
	v_mfma_f32_16x16x32_bf16 v[114:117], v[214:217], v[222:225], v[114:117]
	v_mfma_f32_16x16x32_bf16 v[102:105], v[180:183], v[230:233], v[102:105]
	v_mfma_f32_16x16x32_bf16 v[98:101], v[214:217], v[230:233], v[98:101]
	v_mfma_f32_16x16x32_bf16 v[86:89], v[180:183], v[238:241], v[86:89]
	v_mfma_f32_16x16x32_bf16 v[82:85], v[214:217], v[238:241], v[82:85]
	v_mfma_f32_16x16x32_bf16 v[70:73], v[180:183], v[246:249], v[70:73]
	v_mfma_f32_16x16x32_bf16 v[66:69], v[214:217], v[246:249], v[66:69]
	s_barrier
	s_add_i32 s10, s16, s15
	v_lshl_add_u64 v[154:155], v[156:157], 0, s[34:35]
	s_mov_b32 m0, s10
	ds_read_b128 v[218:221], v213 offset:49152
	ds_read_b128 v[222:225], v213 offset:50176
	ds_read_b128 v[226:229], v213 offset:51200
	ds_read_b128 v[230:233], v213 offset:52224
	ds_read_b128 v[234:237], v213 offset:53248
	ds_read_b128 v[238:241], v213 offset:54272
	ds_read_b128 v[242:245], v213 offset:55296
	ds_read_b128 v[246:249], v213 offset:56320
	global_load_lds_dwordx4 v[154:155], off
	s_add_i32 m0, s10, 0x2000
	s_add_u32 s8, s8, 0x40080
	v_lshl_add_u64 v[154:155], v[188:189], 0, s[34:35]
	s_addc_u32 s9, s9, 0
	s_add_i32 s10, s17, s15
	global_load_lds_dwordx4 v[154:155], off
	v_lshl_add_u64 v[154:155], s[8:9], 0, v[148:149]
	s_mov_b32 m0, s10
	s_nop 0
	global_load_lds_dwordx4 v[154:155], off
	v_lshl_add_u64 v[154:155], s[8:9], 0, v[164:165]
	s_add_i32 m0, s10, 0x2000
	s_nop 0
	global_load_lds_dwordx4 v[154:155], off
	v_lshl_add_u64 v[154:155], v[250:251], 0, s[34:35]
	s_mov_b32 m0, s29
	s_nop 0
	global_load_lds_dwordx4 v[154:155], off
	v_lshl_add_u64 v[154:155], v[252:253], 0, s[34:35]
	s_mov_b32 m0, s28
	s_nop 0
	global_load_lds_dwordx4 v[154:155], off
	s_waitcnt vmcnt(8)
	s_waitcnt lgkmcnt(0)
	s_barrier
	s_waitcnt lgkmcnt(0)
	v_mfma_f32_16x16x32_bf16 v[62:65], v[130:133], v[218:221], v[62:65]
	v_mfma_f32_16x16x32_bf16 v[58:61], v[138:141], v[218:221], v[58:61]
	v_mfma_f32_16x16x32_bf16 v[46:49], v[130:133], v[226:229], v[46:49]
	v_mfma_f32_16x16x32_bf16 v[42:45], v[138:141], v[226:229], v[42:45]
	v_mfma_f32_16x16x32_bf16 v[30:33], v[130:133], v[234:237], v[30:33]
	v_mfma_f32_16x16x32_bf16 v[26:29], v[138:141], v[234:237], v[26:29]
	v_mfma_f32_16x16x32_bf16 v[12:15], v[130:133], v[242:245], v[12:15]
	v_mfma_f32_16x16x32_bf16 v[8:11], v[138:141], v[242:245], v[8:11]
	v_mfma_f32_16x16x32_bf16 v[62:65], v[134:137], v[222:225], v[62:65]
	v_mfma_f32_16x16x32_bf16 v[58:61], v[142:145], v[222:225], v[58:61]
	v_mfma_f32_16x16x32_bf16 v[46:49], v[134:137], v[230:233], v[46:49]
	v_mfma_f32_16x16x32_bf16 v[42:45], v[142:145], v[230:233], v[42:45]
	v_mfma_f32_16x16x32_bf16 v[30:33], v[134:137], v[238:241], v[30:33]
	v_mfma_f32_16x16x32_bf16 v[26:29], v[142:145], v[238:241], v[26:29]
	v_mfma_f32_16x16x32_bf16 v[12:15], v[134:137], v[246:249], v[12:15]
	v_mfma_f32_16x16x32_bf16 v[8:11], v[142:145], v[246:249], v[8:11]
	v_mfma_f32_16x16x32_bf16 v[54:57], v[176:179], v[218:221], v[54:57]
	v_mfma_f32_16x16x32_bf16 v[50:53], v[184:187], v[218:221], v[50:53]
	v_mfma_f32_16x16x32_bf16 v[38:41], v[176:179], v[226:229], v[38:41]
	v_mfma_f32_16x16x32_bf16 v[34:37], v[184:187], v[226:229], v[34:37]
	v_mfma_f32_16x16x32_bf16 v[22:25], v[176:179], v[234:237], v[22:25]
	v_mfma_f32_16x16x32_bf16 v[16:19], v[184:187], v[234:237], v[16:19]
	v_mfma_f32_16x16x32_bf16 v[4:7], v[176:179], v[242:245], v[4:7]
	v_mfma_f32_16x16x32_bf16 v[0:3], v[184:187], v[242:245], v[0:3]
	v_mfma_f32_16x16x32_bf16 v[54:57], v[180:183], v[222:225], v[54:57]
	v_mfma_f32_16x16x32_bf16 v[50:53], v[214:217], v[222:225], v[50:53]
	v_mfma_f32_16x16x32_bf16 v[38:41], v[180:183], v[230:233], v[38:41]
	v_mfma_f32_16x16x32_bf16 v[34:37], v[214:217], v[230:233], v[34:37]
	v_mfma_f32_16x16x32_bf16 v[22:25], v[180:183], v[238:241], v[22:25]
	v_mfma_f32_16x16x32_bf16 v[16:19], v[214:217], v[238:241], v[16:19]
	v_mfma_f32_16x16x32_bf16 v[4:7], v[180:183], v[246:249], v[4:7]
	v_mfma_f32_16x16x32_bf16 v[0:3], v[214:217], v[246:249], v[0:3]
	s_barrier
	s_add_i32 s46, s46, 2
	s_add_u32 s6, s6, 0x100
	s_addc_u32 s7, s7, 0
	s_add_u32 s44, s44, 0x100
	s_addc_u32 s45, s45, 0
	s_cmp_gt_u32 s46, 13
	s_cbranch_scc0 .LBB0_1038
	s_setprio 0
	s_and_b64 vcc, exec, s[54:55]
	s_cbranch_vccz .LBB0_1041
	s_barrier

.LBB0_1597:
	s_ashr_i32 s11, s10, 31
	s_lshl_b64 s[12:13], s[10:11], 19
	s_add_u32 s12, s18, s12
	s_addc_u32 s13, s19, s13
	s_and_b64 s[16:17], s[40:41], exec
	s_cselect_b32 s11, s13, s43
	s_cselect_b32 s15, s12, s42
	s_ashr_i32 s9, s8, 31
	s_lshl_b64 s[16:17], s[8:9], 19
	s_add_u32 s46, s27, s16
	s_addc_u32 s47, s28, s17
	s_and_b64 s[16:17], s[40:41], exec
	s_cselect_b32 s9, s47, s49
	s_cselect_b32 s58, s46, s48
	s_add_u32 s42, s42, 0x40080
	s_addc_u32 s43, s43, 0
	s_add_u32 s59, s48, 0x100
	v_mov_b32_e32 v8, 0
	s_addc_u32 s60, s49, 0
	s_mov_b32 s61, -2
	v_mov_b32_e32 v9, v8
	v_mov_b32_e32 v10, v8
	v_mov_b32_e32 v11, v8
	v_mov_b32_e32 v16, v8
	v_mov_b32_e32 v17, v8
	v_mov_b32_e32 v18, v8
	v_mov_b32_e32 v19, v8
	v_mov_b32_e32 v26, v8
	v_mov_b32_e32 v27, v8
	v_mov_b32_e32 v28, v8
	v_mov_b32_e32 v29, v8
	v_mov_b32_e32 v34, v8
	v_mov_b32_e32 v35, v8
	v_mov_b32_e32 v36, v8
	v_mov_b32_e32 v37, v8
	v_mov_b32_e32 v42, v8
	v_mov_b32_e32 v43, v8
	v_mov_b32_e32 v44, v8
	v_mov_b32_e32 v45, v8
	v_mov_b32_e32 v50, v8
	v_mov_b32_e32 v51, v8
	v_mov_b32_e32 v52, v8
	v_mov_b32_e32 v53, v8
	v_mov_b32_e32 v58, v8
	v_mov_b32_e32 v59, v8
	v_mov_b32_e32 v60, v8
	v_mov_b32_e32 v61, v8
	v_mov_b32_e32 v66, v8
	v_mov_b32_e32 v67, v8
	v_mov_b32_e32 v68, v8
	v_mov_b32_e32 v69, v8
	v_mov_b32_e32 v12, v8
	v_mov_b32_e32 v13, v8
	v_mov_b32_e32 v14, v8
	v_mov_b32_e32 v15, v8
	v_mov_b32_e32 v22, v8
	v_mov_b32_e32 v23, v8
	v_mov_b32_e32 v24, v8
	v_mov_b32_e32 v25, v8
	v_mov_b32_e32 v30, v8
	v_mov_b32_e32 v31, v8
	v_mov_b32_e32 v32, v8
	v_mov_b32_e32 v33, v8
	v_mov_b32_e32 v38, v8
	v_mov_b32_e32 v39, v8
	v_mov_b32_e32 v40, v8
	v_mov_b32_e32 v41, v8
	v_mov_b32_e32 v46, v8
	v_mov_b32_e32 v47, v8
	v_mov_b32_e32 v48, v8
	v_mov_b32_e32 v49, v8
	v_mov_b32_e32 v54, v8
	v_mov_b32_e32 v55, v8
	v_mov_b32_e32 v56, v8
	v_mov_b32_e32 v57, v8
	v_mov_b32_e32 v62, v8
	v_mov_b32_e32 v63, v8
	v_mov_b32_e32 v64, v8
	v_mov_b32_e32 v65, v8
	v_mov_b32_e32 v70, v8
	v_mov_b32_e32 v71, v8
	v_mov_b32_e32 v72, v8
	v_mov_b32_e32 v73, v8
	v_mov_b32_e32 v74, v8
	v_mov_b32_e32 v75, v8
	v_mov_b32_e32 v76, v8
	v_mov_b32_e32 v77, v8
	v_mov_b32_e32 v82, v8
	v_mov_b32_e32 v83, v8
	v_mov_b32_e32 v84, v8
	v_mov_b32_e32 v85, v8
	v_mov_b32_e32 v90, v8
	v_mov_b32_e32 v91, v8
	v_mov_b32_e32 v92, v8
	v_mov_b32_e32 v93, v8
	v_mov_b32_e32 v98, v8
	v_mov_b32_e32 v99, v8
	v_mov_b32_e32 v100, v8
	v_mov_b32_e32 v101, v8
	v_mov_b32_e32 v106, v8
	v_mov_b32_e32 v107, v8
	v_mov_b32_e32 v108, v8
	v_mov_b32_e32 v109, v8
	v_mov_b32_e32 v114, v8
	v_mov_b32_e32 v115, v8
	v_mov_b32_e32 v116, v8
	v_mov_b32_e32 v117, v8
	v_mov_b32_e32 v122, v8
	v_mov_b32_e32 v123, v8
	v_mov_b32_e32 v124, v8
	v_mov_b32_e32 v125, v8
	v_mov_b32_e32 v130, v8
	v_mov_b32_e32 v131, v8
	v_mov_b32_e32 v132, v8
	v_mov_b32_e32 v133, v8
	v_mov_b32_e32 v78, v8
	v_mov_b32_e32 v79, v8
	v_mov_b32_e32 v80, v8
	v_mov_b32_e32 v81, v8
	v_mov_b32_e32 v86, v8
	v_mov_b32_e32 v87, v8
	v_mov_b32_e32 v88, v8
	v_mov_b32_e32 v89, v8
	v_mov_b32_e32 v94, v8
	v_mov_b32_e32 v95, v8
	v_mov_b32_e32 v96, v8
	v_mov_b32_e32 v97, v8
	v_mov_b32_e32 v102, v8
	v_mov_b32_e32 v103, v8
	v_mov_b32_e32 v104, v8
	v_mov_b32_e32 v105, v8
	v_mov_b32_e32 v110, v8
	v_mov_b32_e32 v111, v8
	v_mov_b32_e32 v112, v8
	v_mov_b32_e32 v113, v8
	v_mov_b32_e32 v118, v8
	v_mov_b32_e32 v119, v8
	v_mov_b32_e32 v120, v8
	v_mov_b32_e32 v121, v8
	v_mov_b32_e32 v126, v8
	v_mov_b32_e32 v127, v8
	v_mov_b32_e32 v128, v8
	v_mov_b32_e32 v129, v8
	v_mov_b32_e32 v134, v8
	v_mov_b32_e32 v135, v8
	v_mov_b32_e32 v136, v8
	v_mov_b32_e32 v137, v8
	s_cmp_lg_u64 s[6:7], 0
	s_cbranch_scc1 .Lprio_skip_gu
	s_setprio 1
.Lprio_skip_gu:
.LBB0_1598:
	s_add_u32 s16, s42, 0xfffc0080
	s_addc_u32 s17, s43, -1
	s_add_i32 s67, 0, 0x10000
	s_cmp_eq_u32 s61, 12
	s_cselect_b32 s51, s11, s17
	s_cselect_b32 s50, s15, s16
	s_cselect_b32 s49, s9, s60
	s_cselect_b32 s48, s58, s59
	s_add_i32 s68, 0, 0x14000
	v_add_u32_e32 v142, s67, v189
	v_add_u32_e32 v154, s68, v189
	ds_read_b128 v[0:3], v142
	ds_read_b128 v[4:7], v142 offset:1024
	ds_read_b128 v[138:141], v142 offset:2048
	ds_read_b128 v[142:145], v142 offset:3072
	ds_read_b128 v[146:149], v154
	ds_read_b128 v[176:179], v154 offset:1024
	ds_read_b128 v[180:183], v154 offset:2048
	ds_read_b128 v[184:187], v154 offset:3072
	v_lshl_add_u64 v[244:245], s[42:43], 0, v[172:173]
	s_add_i32 m0, s29, 0xc000
	ds_read_b128 v[212:215], v211
	ds_read_b128 v[216:219], v211 offset:1024
	ds_read_b128 v[220:223], v211 offset:2048
	ds_read_b128 v[224:227], v211 offset:3072
	ds_read_b128 v[228:231], v211 offset:4096
	ds_read_b128 v[232:235], v211 offset:5120
	ds_read_b128 v[236:239], v211 offset:6144
	ds_read_b128 v[240:243], v211 offset:7168
	global_load_lds_dwordx4 v[244:245], off
	v_lshl_add_u64 v[244:245], s[42:43], 0, v[174:175]
	s_add_i32 m0, s29, 0xe000
	s_nop 0
	global_load_lds_dwordx4 v[244:245], off
	s_waitcnt vmcnt(8)
	s_waitcnt lgkmcnt(0)
	s_barrier
	s_waitcnt lgkmcnt(0)
	v_mfma_f32_16x16x32_bf16 v[134:137], v[0:3], v[212:215], v[134:137]
	v_mfma_f32_16x16x32_bf16 v[126:129], v[138:141], v[212:215], v[126:129]
	v_mfma_f32_16x16x32_bf16 v[118:121], v[0:3], v[220:223], v[118:121]
	v_mfma_f32_16x16x32_bf16 v[110:113], v[138:141], v[220:223], v[110:113]
	v_mfma_f32_16x16x32_bf16 v[102:105], v[0:3], v[228:231], v[102:105]
	v_mfma_f32_16x16x32_bf16 v[94:97], v[138:141], v[228:231], v[94:97]
	v_mfma_f32_16x16x32_bf16 v[86:89], v[0:3], v[236:239], v[86:89]
	v_mfma_f32_16x16x32_bf16 v[78:81], v[138:141], v[236:239], v[78:81]
	v_mfma_f32_16x16x32_bf16 v[134:137], v[4:7], v[216:219], v[134:137]
	v_mfma_f32_16x16x32_bf16 v[126:129], v[142:145], v[216:219], v[126:129]
	v_mfma_f32_16x16x32_bf16 v[118:121], v[4:7], v[224:227], v[118:121]
	v_mfma_f32_16x16x32_bf16 v[110:113], v[142:145], v[224:227], v[110:113]
	v_mfma_f32_16x16x32_bf16 v[102:105], v[4:7], v[232:235], v[102:105]
	v_mfma_f32_16x16x32_bf16 v[94:97], v[142:145], v[232:235], v[94:97]
	v_mfma_f32_16x16x32_bf16 v[86:89], v[4:7], v[240:243], v[86:89]
	v_mfma_f32_16x16x32_bf16 v[78:81], v[142:145], v[240:243], v[78:81]
	v_mfma_f32_16x16x32_bf16 v[130:133], v[146:149], v[212:215], v[130:133]
	v_mfma_f32_16x16x32_bf16 v[122:125], v[180:183], v[212:215], v[122:125]
	v_mfma_f32_16x16x32_bf16 v[114:117], v[146:149], v[220:223], v[114:117]
	v_mfma_f32_16x16x32_bf16 v[106:109], v[180:183], v[220:223], v[106:109]
	v_mfma_f32_16x16x32_bf16 v[98:101], v[146:149], v[228:231], v[98:101]
	v_mfma_f32_16x16x32_bf16 v[90:93], v[180:183], v[228:231], v[90:93]
	v_mfma_f32_16x16x32_bf16 v[82:85], v[146:149], v[236:239], v[82:85]
	v_mfma_f32_16x16x32_bf16 v[74:77], v[180:183], v[236:239], v[74:77]
	v_mfma_f32_16x16x32_bf16 v[130:133], v[176:179], v[216:219], v[130:133]
	v_mfma_f32_16x16x32_bf16 v[122:125], v[184:187], v[216:219], v[122:125]
	v_mfma_f32_16x16x32_bf16 v[114:117], v[176:179], v[224:227], v[114:117]
	v_mfma_f32_16x16x32_bf16 v[106:109], v[184:187], v[224:227], v[106:109]
	v_mfma_f32_16x16x32_bf16 v[98:101], v[176:179], v[232:235], v[98:101]
	v_mfma_f32_16x16x32_bf16 v[90:93], v[184:187], v[232:235], v[90:93]
	v_mfma_f32_16x16x32_bf16 v[82:85], v[176:179], v[240:243], v[82:85]
	v_mfma_f32_16x16x32_bf16 v[74:77], v[184:187], v[240:243], v[74:77]
	s_barrier
	s_add_i32 s16, s67, s26
	v_lshl_add_u64 v[244:245], s[48:49], 0, v[164:165]
	s_mov_b32 m0, s16
	ds_read_b128 v[212:215], v211 offset:16384
	ds_read_b128 v[216:219], v211 offset:17408
	ds_read_b128 v[220:223], v211 offset:18432
	ds_read_b128 v[224:227], v211 offset:19456
	ds_read_b128 v[228:231], v211 offset:20480
	ds_read_b128 v[232:235], v211 offset:21504
	ds_read_b128 v[236:239], v211 offset:22528
	ds_read_b128 v[240:243], v211 offset:23552
	global_load_lds_dwordx4 v[244:245], off
	s_add_i32 m0, s16, 0x2000
	s_add_u32 s16, s48, 0x40000
	v_lshl_add_u64 v[246:247], s[48:49], 0, v[168:169]
	s_addc_u32 s17, s49, 0
	s_add_i32 s67, s68, s26
	global_load_lds_dwordx4 v[246:247], off
	v_lshl_add_u64 v[248:249], s[16:17], 0, v[164:165]
	s_mov_b32 m0, s67
	v_lshl_add_u64 v[250:251], s[50:51], 0, v[166:167]
	global_load_lds_dwordx4 v[248:249], off
	v_lshl_add_u64 v[248:249], s[16:17], 0, v[168:169]
	s_add_i32 m0, s67, 0x2000
	s_nop 0
	global_load_lds_dwordx4 v[248:249], off
	v_lshl_add_u64 v[248:249], s[50:51], 0, v[162:163]
	s_mov_b32 m0, s29
	s_nop 0
	global_load_lds_dwordx4 v[248:249], off
	s_mov_b32 m0, s30
	s_nop 0
	global_load_lds_dwordx4 v[250:251], off
	s_waitcnt vmcnt(8)
	s_waitcnt lgkmcnt(0)
	s_barrier
	s_waitcnt lgkmcnt(0)
	v_mfma_f32_16x16x32_bf16 v[70:73], v[0:3], v[212:215], v[70:73]
	v_mfma_f32_16x16x32_bf16 v[62:65], v[138:141], v[212:215], v[62:65]
	v_mfma_f32_16x16x32_bf16 v[54:57], v[0:3], v[220:223], v[54:57]
	v_mfma_f32_16x16x32_bf16 v[46:49], v[138:141], v[220:223], v[46:49]
	v_mfma_f32_16x16x32_bf16 v[38:41], v[0:3], v[228:231], v[38:41]
	v_mfma_f32_16x16x32_bf16 v[30:33], v[138:141], v[228:231], v[30:33]
	v_mfma_f32_16x16x32_bf16 v[0:3], v[0:3], v[236:239], v[22:25]
	v_mfma_f32_16x16x32_bf16 v[70:73], v[4:7], v[216:219], v[70:73]
	v_mfma_f32_16x16x32_bf16 v[62:65], v[142:145], v[216:219], v[62:65]
	v_mfma_f32_16x16x32_bf16 v[54:57], v[4:7], v[224:227], v[54:57]
	v_mfma_f32_16x16x32_bf16 v[46:49], v[142:145], v[224:227], v[46:49]
	v_mfma_f32_16x16x32_bf16 v[38:41], v[4:7], v[232:235], v[38:41]
	v_mfma_f32_16x16x32_bf16 v[30:33], v[142:145], v[232:235], v[30:33]
	v_mfma_f32_16x16x32_bf16 v[0:3], v[4:7], v[240:243], v[0:3]
	v_mfma_f32_16x16x32_bf16 v[4:7], v[138:141], v[236:239], v[12:15]
	v_mfma_f32_16x16x32_bf16 v[4:7], v[142:145], v[240:243], v[4:7]
	v_mfma_f32_16x16x32_bf16 v[12:15], v[146:149], v[212:215], v[66:69]
	v_mfma_f32_16x16x32_bf16 v[66:69], v[176:179], v[216:219], v[12:15]
	v_mfma_f32_16x16x32_bf16 v[12:15], v[180:183], v[212:215], v[58:61]
	v_mfma_f32_16x16x32_bf16 v[58:61], v[184:187], v[216:219], v[12:15]
	v_mfma_f32_16x16x32_bf16 v[12:15], v[146:149], v[220:223], v[50:53]
	v_mfma_f32_16x16x32_bf16 v[50:53], v[176:179], v[224:227], v[12:15]
	v_mfma_f32_16x16x32_bf16 v[12:15], v[180:183], v[220:223], v[42:45]
	v_mfma_f32_16x16x32_bf16 v[42:45], v[184:187], v[224:227], v[12:15]
	v_mfma_f32_16x16x32_bf16 v[12:15], v[146:149], v[228:231], v[34:37]
	v_mfma_f32_16x16x32_bf16 v[34:37], v[176:179], v[232:235], v[12:15]
	v_mfma_f32_16x16x32_bf16 v[12:15], v[180:183], v[228:231], v[26:29]
	v_mfma_f32_16x16x32_bf16 v[26:29], v[184:187], v[232:235], v[12:15]
	v_mfma_f32_16x16x32_bf16 v[12:15], v[146:149], v[236:239], v[16:19]
	v_mfma_f32_16x16x32_bf16 v[8:11], v[180:183], v[236:239], v[8:11]
	v_mfma_f32_16x16x32_bf16 v[16:19], v[176:179], v[240:243], v[12:15]
	v_mfma_f32_16x16x32_bf16 v[8:11], v[184:187], v[240:243], v[8:11]
	s_barrier
	s_add_i32 s67, 0, 0x18000
	s_add_i32 s68, 0, 0x1c000
	v_add_u32_e32 v142, s67, v189
	v_add_u32_e32 v154, s68, v189
	ds_read_b128 v[12:15], v142
	ds_read_b128 v[22:25], v142 offset:1024
	ds_read_b128 v[138:141], v142 offset:2048
	ds_read_b128 v[142:145], v142 offset:3072
	ds_read_b128 v[146:149], v154
	ds_read_b128 v[176:179], v154 offset:1024
	ds_read_b128 v[180:183], v154 offset:2048
	ds_read_b128 v[184:187], v154 offset:3072
	s_add_u32 s16, s50, 0x40000
	s_addc_u32 s17, s51, 0
	s_mov_b32 m0, s33
	v_lshl_add_u64 v[252:253], s[16:17], 0, v[162:163]
	ds_read_b128 v[212:215], v211 offset:32768
	ds_read_b128 v[216:219], v211 offset:33792
	ds_read_b128 v[220:223], v211 offset:34816
	ds_read_b128 v[224:227], v211 offset:35840
	ds_read_b128 v[228:231], v211 offset:36864
	ds_read_b128 v[232:235], v211 offset:37888
	ds_read_b128 v[236:239], v211 offset:38912
	ds_read_b128 v[240:243], v211 offset:39936
	global_load_lds_dwordx4 v[252:253], off
	v_lshl_add_u64 v[252:253], s[16:17], 0, v[166:167]
	s_mov_b32 m0, s52
	s_nop 0
	global_load_lds_dwordx4 v[252:253], off
	s_waitcnt vmcnt(8)
	s_waitcnt lgkmcnt(0)
	s_barrier
	s_waitcnt lgkmcnt(0)
	v_mfma_f32_16x16x32_bf16 v[134:137], v[12:15], v[212:215], v[134:137]
	v_mfma_f32_16x16x32_bf16 v[126:129], v[138:141], v[212:215], v[126:129]
	v_mfma_f32_16x16x32_bf16 v[118:121], v[12:15], v[220:223], v[118:121]
	v_mfma_f32_16x16x32_bf16 v[110:113], v[138:141], v[220:223], v[110:113]
	v_mfma_f32_16x16x32_bf16 v[102:105], v[12:15], v[228:231], v[102:105]
	v_mfma_f32_16x16x32_bf16 v[94:97], v[138:141], v[228:231], v[94:97]
	v_mfma_f32_16x16x32_bf16 v[86:89], v[12:15], v[236:239], v[86:89]
	v_mfma_f32_16x16x32_bf16 v[78:81], v[138:141], v[236:239], v[78:81]
	v_mfma_f32_16x16x32_bf16 v[134:137], v[22:25], v[216:219], v[134:137]
	v_mfma_f32_16x16x32_bf16 v[126:129], v[142:145], v[216:219], v[126:129]
	v_mfma_f32_16x16x32_bf16 v[118:121], v[22:25], v[224:227], v[118:121]
	v_mfma_f32_16x16x32_bf16 v[110:113], v[142:145], v[224:227], v[110:113]
	v_mfma_f32_16x16x32_bf16 v[102:105], v[22:25], v[232:235], v[102:105]
	v_mfma_f32_16x16x32_bf16 v[94:97], v[142:145], v[232:235], v[94:97]
	v_mfma_f32_16x16x32_bf16 v[86:89], v[22:25], v[240:243], v[86:89]
	v_mfma_f32_16x16x32_bf16 v[78:81], v[142:145], v[240:243], v[78:81]
	v_mfma_f32_16x16x32_bf16 v[130:133], v[146:149], v[212:215], v[130:133]
	v_mfma_f32_16x16x32_bf16 v[122:125], v[180:183], v[212:215], v[122:125]
	v_mfma_f32_16x16x32_bf16 v[114:117], v[146:149], v[220:223], v[114:117]
	v_mfma_f32_16x16x32_bf16 v[106:109], v[180:183], v[220:223], v[106:109]
	v_mfma_f32_16x16x32_bf16 v[98:101], v[146:149], v[228:231], v[98:101]
	v_mfma_f32_16x16x32_bf16 v[90:93], v[180:183], v[228:231], v[90:93]
	v_mfma_f32_16x16x32_bf16 v[82:85], v[146:149], v[236:239], v[82:85]
	v_mfma_f32_16x16x32_bf16 v[74:77], v[180:183], v[236:239], v[74:77]
	v_mfma_f32_16x16x32_bf16 v[130:133], v[176:179], v[216:219], v[130:133]
	v_mfma_f32_16x16x32_bf16 v[122:125], v[184:187], v[216:219], v[122:125]
	v_mfma_f32_16x16x32_bf16 v[114:117], v[176:179], v[224:227], v[114:117]
	v_mfma_f32_16x16x32_bf16 v[106:109], v[184:187], v[224:227], v[106:109]
	v_mfma_f32_16x16x32_bf16 v[98:101], v[176:179], v[232:235], v[98:101]
	v_mfma_f32_16x16x32_bf16 v[90:93], v[184:187], v[232:235], v[90:93]
	v_mfma_f32_16x16x32_bf16 v[82:85], v[176:179], v[240:243], v[82:85]
	v_mfma_f32_16x16x32_bf16 v[74:77], v[184:187], v[240:243], v[74:77]
	s_barrier
	s_add_i32 s16, s67, s26
	v_lshl_add_u64 v[244:245], v[244:245], 0, s[34:35]
	s_mov_b32 m0, s16
	ds_read_b128 v[212:215], v211 offset:49152
	ds_read_b128 v[216:219], v211 offset:50176
	ds_read_b128 v[220:223], v211 offset:51200
	ds_read_b128 v[224:227], v211 offset:52224
	ds_read_b128 v[228:231], v211 offset:53248
	ds_read_b128 v[232:235], v211 offset:54272
	ds_read_b128 v[236:239], v211 offset:55296
	ds_read_b128 v[240:243], v211 offset:56320
	global_load_lds_dwordx4 v[244:245], off
	s_add_i32 m0, s16, 0x2000
	s_add_u32 s16, s48, 0x40080
	v_lshl_add_u64 v[244:245], v[246:247], 0, s[34:35]
	s_addc_u32 s17, s49, 0
	s_add_i32 s48, s68, s26
	global_load_lds_dwordx4 v[244:245], off
	v_lshl_add_u64 v[244:245], s[16:17], 0, v[164:165]
	s_mov_b32 m0, s48
	s_nop 0
	global_load_lds_dwordx4 v[244:245], off
	v_lshl_add_u64 v[244:245], s[16:17], 0, v[168:169]
	s_add_i32 m0, s48, 0x2000
	s_nop 0
	global_load_lds_dwordx4 v[244:245], off
	v_lshl_add_u64 v[244:245], v[248:249], 0, s[34:35]
	s_mov_b32 m0, s53
	s_nop 0
	global_load_lds_dwordx4 v[244:245], off
	v_lshl_add_u64 v[244:245], v[250:251], 0, s[34:35]
	s_mov_b32 m0, s54
	s_nop 0
	global_load_lds_dwordx4 v[244:245], off
	s_waitcnt vmcnt(8)
	s_waitcnt lgkmcnt(0)
	s_barrier
	s_waitcnt lgkmcnt(0)
	v_mfma_f32_16x16x32_bf16 v[70:73], v[12:15], v[212:215], v[70:73]
	v_mfma_f32_16x16x32_bf16 v[54:57], v[12:15], v[220:223], v[54:57]
	v_mfma_f32_16x16x32_bf16 v[38:41], v[12:15], v[228:231], v[38:41]
	v_mfma_f32_16x16x32_bf16 v[0:3], v[12:15], v[236:239], v[0:3]
	v_mfma_f32_16x16x32_bf16 v[70:73], v[22:25], v[216:219], v[70:73]
	v_mfma_f32_16x16x32_bf16 v[62:65], v[138:141], v[212:215], v[62:65]
	v_mfma_f32_16x16x32_bf16 v[54:57], v[22:25], v[224:227], v[54:57]
	v_mfma_f32_16x16x32_bf16 v[46:49], v[138:141], v[220:223], v[46:49]
	v_mfma_f32_16x16x32_bf16 v[38:41], v[22:25], v[232:235], v[38:41]
	v_mfma_f32_16x16x32_bf16 v[30:33], v[138:141], v[228:231], v[30:33]
	v_mfma_f32_16x16x32_bf16 v[22:25], v[22:25], v[240:243], v[0:3]
	v_mfma_f32_16x16x32_bf16 v[0:3], v[138:141], v[236:239], v[4:7]
	v_mfma_f32_16x16x32_bf16 v[62:65], v[142:145], v[216:219], v[62:65]
	v_mfma_f32_16x16x32_bf16 v[46:49], v[142:145], v[224:227], v[46:49]
	v_mfma_f32_16x16x32_bf16 v[30:33], v[142:145], v[232:235], v[30:33]
	v_mfma_f32_16x16x32_bf16 v[12:15], v[142:145], v[240:243], v[0:3]
	v_mfma_f32_16x16x32_bf16 v[0:3], v[146:149], v[212:215], v[66:69]
	v_mfma_f32_16x16x32_bf16 v[66:69], v[176:179], v[216:219], v[0:3]
	v_mfma_f32_16x16x32_bf16 v[0:3], v[180:183], v[212:215], v[58:61]
	v_mfma_f32_16x16x32_bf16 v[58:61], v[184:187], v[216:219], v[0:3]
	v_mfma_f32_16x16x32_bf16 v[0:3], v[146:149], v[220:223], v[50:53]
	v_mfma_f32_16x16x32_bf16 v[50:53], v[176:179], v[224:227], v[0:3]
	v_mfma_f32_16x16x32_bf16 v[0:3], v[180:183], v[220:223], v[42:45]
	v_mfma_f32_16x16x32_bf16 v[42:45], v[184:187], v[224:227], v[0:3]
	v_mfma_f32_16x16x32_bf16 v[0:3], v[146:149], v[228:231], v[34:37]
	v_mfma_f32_16x16x32_bf16 v[34:37], v[176:179], v[232:235], v[0:3]
	v_mfma_f32_16x16x32_bf16 v[0:3], v[180:183], v[228:231], v[26:29]
	v_mfma_f32_16x16x32_bf16 v[26:29], v[184:187], v[232:235], v[0:3]
	v_mfma_f32_16x16x32_bf16 v[0:3], v[146:149], v[236:239], v[16:19]
	v_mfma_f32_16x16x32_bf16 v[16:19], v[176:179], v[240:243], v[0:3]
	v_mfma_f32_16x16x32_bf16 v[0:3], v[180:183], v[236:239], v[8:11]
	v_mfma_f32_16x16x32_bf16 v[8:11], v[184:187], v[240:243], v[0:3]
	s_barrier
	s_add_i32 s61, s61, 2
	s_add_u32 s42, s42, 0x100
	s_addc_u32 s43, s43, 0
	s_add_u32 s59, s59, 0x100
	s_addc_u32 s60, s60, 0
	s_cmp_gt_u32 s61, 13
	s_cbranch_scc0 .LBB0_1598
	s_setprio 0
	s_and_b64 vcc, exec, s[6:7]
	s_cbranch_vccz .LBB0_1601
	s_barrier

.LBB0_2065:
	s_add_u32 s56, s26, 0x100
	v_mov_b32_e32 v0, 0
	s_addc_u32 s57, s27, 0
	s_mov_b32 s58, -2
	s_waitcnt lgkmcnt(0)
	v_mov_b32_e32 v1, v0
	v_mov_b32_e32 v2, v0
	v_mov_b32_e32 v3, v0
	v_mov_b32_e32 v4, v0
	v_mov_b32_e32 v5, v0
	v_mov_b32_e32 v6, v0
	v_mov_b32_e32 v7, v0
	v_mov_b32_e32 v16, v0
	v_mov_b32_e32 v17, v0
	v_mov_b32_e32 v18, v0
	v_mov_b32_e32 v19, v0
	v_mov_b32_e32 v22, v0
	v_mov_b32_e32 v23, v0
	v_mov_b32_e32 v24, v0
	v_mov_b32_e32 v25, v0
	v_mov_b32_e32 v34, v0
	v_mov_b32_e32 v35, v0
	v_mov_b32_e32 v36, v0
	v_mov_b32_e32 v37, v0
	v_mov_b32_e32 v38, v0
	v_mov_b32_e32 v39, v0
	v_mov_b32_e32 v40, v0
	v_mov_b32_e32 v41, v0
	v_mov_b32_e32 v50, v0
	v_mov_b32_e32 v51, v0
	v_mov_b32_e32 v52, v0
	v_mov_b32_e32 v53, v0
	v_mov_b32_e32 v54, v0
	v_mov_b32_e32 v55, v0
	v_mov_b32_e32 v56, v0
	v_mov_b32_e32 v57, v0
	v_mov_b32_e32 v8, v0
	v_mov_b32_e32 v9, v0
	v_mov_b32_e32 v10, v0
	v_mov_b32_e32 v11, v0
	v_mov_b32_e32 v12, v0
	v_mov_b32_e32 v13, v0
	v_mov_b32_e32 v14, v0
	v_mov_b32_e32 v15, v0
	v_mov_b32_e32 v26, v0
	v_mov_b32_e32 v27, v0
	v_mov_b32_e32 v28, v0
	v_mov_b32_e32 v29, v0
	v_mov_b32_e32 v30, v0
	v_mov_b32_e32 v31, v0
	v_mov_b32_e32 v32, v0
	v_mov_b32_e32 v33, v0
	v_mov_b32_e32 v42, v0
	v_mov_b32_e32 v43, v0
	v_mov_b32_e32 v44, v0
	v_mov_b32_e32 v45, v0
	v_mov_b32_e32 v46, v0
	v_mov_b32_e32 v47, v0
	v_mov_b32_e32 v48, v0
	v_mov_b32_e32 v49, v0
	v_mov_b32_e32 v58, v0
	v_mov_b32_e32 v59, v0
	v_mov_b32_e32 v60, v0
	v_mov_b32_e32 v61, v0
	v_mov_b32_e32 v62, v0
	v_mov_b32_e32 v63, v0
	v_mov_b32_e32 v64, v0
	v_mov_b32_e32 v65, v0
	v_mov_b32_e32 v66, v0
	v_mov_b32_e32 v67, v0
	v_mov_b32_e32 v68, v0
	v_mov_b32_e32 v69, v0
	v_mov_b32_e32 v70, v0
	v_mov_b32_e32 v71, v0
	v_mov_b32_e32 v72, v0
	v_mov_b32_e32 v73, v0
	v_mov_b32_e32 v82, v0
	v_mov_b32_e32 v83, v0
	v_mov_b32_e32 v84, v0
	v_mov_b32_e32 v85, v0
	v_mov_b32_e32 v86, v0
	v_mov_b32_e32 v87, v0
	v_mov_b32_e32 v88, v0
	v_mov_b32_e32 v89, v0
	v_mov_b32_e32 v98, v0
	v_mov_b32_e32 v99, v0
	v_mov_b32_e32 v100, v0
	v_mov_b32_e32 v101, v0
	v_mov_b32_e32 v102, v0
	v_mov_b32_e32 v103, v0
	v_mov_b32_e32 v104, v0
	v_mov_b32_e32 v105, v0
	v_mov_b32_e32 v114, v0
	v_mov_b32_e32 v115, v0
	v_mov_b32_e32 v116, v0
	v_mov_b32_e32 v117, v0
	v_mov_b32_e32 v118, v0
	v_mov_b32_e32 v119, v0
	v_mov_b32_e32 v120, v0
	v_mov_b32_e32 v121, v0
	v_mov_b32_e32 v74, v0
	v_mov_b32_e32 v75, v0
	v_mov_b32_e32 v76, v0
	v_mov_b32_e32 v77, v0
	v_mov_b32_e32 v78, v0
	v_mov_b32_e32 v79, v0
	v_mov_b32_e32 v80, v0
	v_mov_b32_e32 v81, v0
	v_mov_b32_e32 v90, v0
	v_mov_b32_e32 v91, v0
	v_mov_b32_e32 v92, v0
	v_mov_b32_e32 v93, v0
	v_mov_b32_e32 v94, v0
	v_mov_b32_e32 v95, v0
	v_mov_b32_e32 v96, v0
	v_mov_b32_e32 v97, v0
	v_mov_b32_e32 v106, v0
	v_mov_b32_e32 v107, v0
	v_mov_b32_e32 v108, v0
	v_mov_b32_e32 v109, v0
	v_mov_b32_e32 v110, v0
	v_mov_b32_e32 v111, v0
	v_mov_b32_e32 v112, v0
	v_mov_b32_e32 v113, v0
	v_mov_b32_e32 v122, v0
	v_mov_b32_e32 v123, v0
	v_mov_b32_e32 v124, v0
	v_mov_b32_e32 v125, v0
	v_mov_b32_e32 v126, v0
	v_mov_b32_e32 v127, v0
	v_mov_b32_e32 v128, v0
	v_mov_b32_e32 v129, v0
	s_cmp_lg_u64 s[8:9], 0
	s_cbranch_scc1 .Lprio_skip_down
	s_setprio 1
.Lprio_skip_down:
.LBB0_2066:
	s_add_u32 s26, s14, 0x100
	s_addc_u32 s27, s15, 0
	s_add_i32 s16, 0, 0x10000
	s_cmp_eq_u32 s58, 40
	s_cselect_b32 s45, s11, s27
	s_cselect_b32 s44, s10, s26
	v_add_u32_e32 v154, s16, v163
	s_cselect_b32 s43, s13, s57
	s_cselect_b32 s42, s12, s56
	s_add_i32 s17, 0, 0x14000
	ds_read_b128 v[144:147], v154
	ds_read_b128 v[168:171], v154 offset:1024
	ds_read_b128 v[172:175], v154 offset:2048
	ds_read_b128 v[176:179], v154 offset:3072
	v_add_u32_e32 v154, s17, v163
	ds_read_b128 v[180:183], v154
	ds_read_b128 v[184:187], v154 offset:1024
	ds_read_b128 v[208:211], v154 offset:2048
	ds_read_b128 v[212:215], v154 offset:3072
	v_lshl_add_u64 v[188:189], s[14:15], 0, v[140:141]
	s_add_i32 m0, s29, 0xc000
	ds_read_b128 v[216:219], v166
	ds_read_b128 v[220:223], v166 offset:1024
	ds_read_b128 v[224:227], v166 offset:2048
	ds_read_b128 v[228:231], v166 offset:3072
	ds_read_b128 v[232:235], v166 offset:4096
	ds_read_b128 v[236:239], v166 offset:5120
	ds_read_b128 v[240:243], v166 offset:6144
	ds_read_b128 v[244:247], v166 offset:7168
	global_load_lds_dwordx4 v[188:189], off
	v_lshl_add_u64 v[188:189], s[14:15], 0, v[142:143]
	s_add_i32 m0, s29, 0xe000
	s_nop 0
	global_load_lds_dwordx4 v[188:189], off
	s_waitcnt vmcnt(8)
	s_waitcnt lgkmcnt(0)
	s_barrier
	s_waitcnt lgkmcnt(0)
	v_mfma_f32_16x16x32_bf16 v[126:129], v[144:147], v[216:219], v[126:129]
	v_mfma_f32_16x16x32_bf16 v[122:125], v[172:175], v[216:219], v[122:125]
	v_mfma_f32_16x16x32_bf16 v[110:113], v[144:147], v[224:227], v[110:113]
	v_mfma_f32_16x16x32_bf16 v[106:109], v[172:175], v[224:227], v[106:109]
	v_mfma_f32_16x16x32_bf16 v[94:97], v[144:147], v[232:235], v[94:97]
	v_mfma_f32_16x16x32_bf16 v[90:93], v[172:175], v[232:235], v[90:93]
	v_mfma_f32_16x16x32_bf16 v[78:81], v[144:147], v[240:243], v[78:81]
	v_mfma_f32_16x16x32_bf16 v[74:77], v[172:175], v[240:243], v[74:77]
	v_mfma_f32_16x16x32_bf16 v[126:129], v[168:171], v[220:223], v[126:129]
	v_mfma_f32_16x16x32_bf16 v[122:125], v[176:179], v[220:223], v[122:125]
	v_mfma_f32_16x16x32_bf16 v[110:113], v[168:171], v[228:231], v[110:113]
	v_mfma_f32_16x16x32_bf16 v[106:109], v[176:179], v[228:231], v[106:109]
	v_mfma_f32_16x16x32_bf16 v[94:97], v[168:171], v[236:239], v[94:97]
	v_mfma_f32_16x16x32_bf16 v[90:93], v[176:179], v[236:239], v[90:93]
	v_mfma_f32_16x16x32_bf16 v[78:81], v[168:171], v[244:247], v[78:81]
	v_mfma_f32_16x16x32_bf16 v[74:77], v[176:179], v[244:247], v[74:77]
	v_mfma_f32_16x16x32_bf16 v[118:121], v[180:183], v[216:219], v[118:121]
	v_mfma_f32_16x16x32_bf16 v[114:117], v[208:211], v[216:219], v[114:117]
	v_mfma_f32_16x16x32_bf16 v[102:105], v[180:183], v[224:227], v[102:105]
	v_mfma_f32_16x16x32_bf16 v[98:101], v[208:211], v[224:227], v[98:101]
	v_mfma_f32_16x16x32_bf16 v[86:89], v[180:183], v[232:235], v[86:89]
	v_mfma_f32_16x16x32_bf16 v[82:85], v[208:211], v[232:235], v[82:85]
	v_mfma_f32_16x16x32_bf16 v[70:73], v[180:183], v[240:243], v[70:73]
	v_mfma_f32_16x16x32_bf16 v[66:69], v[208:211], v[240:243], v[66:69]
	v_mfma_f32_16x16x32_bf16 v[118:121], v[184:187], v[220:223], v[118:121]
	v_mfma_f32_16x16x32_bf16 v[114:117], v[212:215], v[220:223], v[114:117]
	v_mfma_f32_16x16x32_bf16 v[102:105], v[184:187], v[228:231], v[102:105]
	v_mfma_f32_16x16x32_bf16 v[98:101], v[212:215], v[228:231], v[98:101]
	v_mfma_f32_16x16x32_bf16 v[86:89], v[184:187], v[236:239], v[86:89]
	v_mfma_f32_16x16x32_bf16 v[82:85], v[212:215], v[236:239], v[82:85]
	v_mfma_f32_16x16x32_bf16 v[70:73], v[184:187], v[244:247], v[70:73]
	v_mfma_f32_16x16x32_bf16 v[66:69], v[212:215], v[244:247], v[66:69]
	s_barrier
	s_add_i32 s14, s16, s28
	v_lshl_add_u64 v[188:189], s[42:43], 0, v[132:133]
	s_mov_b32 m0, s14
	ds_read_b128 v[216:219], v166 offset:16384
	ds_read_b128 v[220:223], v166 offset:17408
	ds_read_b128 v[224:227], v166 offset:18432
	ds_read_b128 v[228:231], v166 offset:19456
	ds_read_b128 v[232:235], v166 offset:20480
	ds_read_b128 v[236:239], v166 offset:21504
	ds_read_b128 v[240:243], v166 offset:22528
	ds_read_b128 v[244:247], v166 offset:23552
	global_load_lds_dwordx4 v[188:189], off
	s_add_i32 m0, s14, 0x2000
	s_add_u32 s14, s42, 0xb0000
	v_lshl_add_u64 v[248:249], s[42:43], 0, v[136:137]
	s_addc_u32 s15, s43, 0
	s_add_i32 s16, s17, s28
	global_load_lds_dwordx4 v[248:249], off
	v_lshl_add_u64 v[250:251], s[14:15], 0, v[132:133]
	s_mov_b32 m0, s16
	v_lshl_add_u64 v[252:253], s[44:45], 0, v[134:135]
	global_load_lds_dwordx4 v[250:251], off
	v_lshl_add_u64 v[250:251], s[14:15], 0, v[136:137]
	s_add_i32 m0, s16, 0x2000
	s_nop 0
	global_load_lds_dwordx4 v[250:251], off
	v_lshl_add_u64 v[250:251], s[44:45], 0, v[130:131]
	s_mov_b32 m0, s29
	s_nop 0
	global_load_lds_dwordx4 v[250:251], off
	s_mov_b32 m0, s30
	s_nop 0
	global_load_lds_dwordx4 v[252:253], off
	s_waitcnt vmcnt(8)
	s_waitcnt lgkmcnt(0)
	s_barrier
	s_waitcnt lgkmcnt(0)
	v_mfma_f32_16x16x32_bf16 v[62:65], v[144:147], v[216:219], v[62:65]
	v_mfma_f32_16x16x32_bf16 v[58:61], v[172:175], v[216:219], v[58:61]
	v_mfma_f32_16x16x32_bf16 v[46:49], v[144:147], v[224:227], v[46:49]
	v_mfma_f32_16x16x32_bf16 v[42:45], v[172:175], v[224:227], v[42:45]
	v_mfma_f32_16x16x32_bf16 v[30:33], v[144:147], v[232:235], v[30:33]
	v_mfma_f32_16x16x32_bf16 v[26:29], v[172:175], v[232:235], v[26:29]
	v_mfma_f32_16x16x32_bf16 v[12:15], v[144:147], v[240:243], v[12:15]
	v_mfma_f32_16x16x32_bf16 v[8:11], v[172:175], v[240:243], v[8:11]
	v_mfma_f32_16x16x32_bf16 v[62:65], v[168:171], v[220:223], v[62:65]
	v_mfma_f32_16x16x32_bf16 v[58:61], v[176:179], v[220:223], v[58:61]
	v_mfma_f32_16x16x32_bf16 v[46:49], v[168:171], v[228:231], v[46:49]
	v_mfma_f32_16x16x32_bf16 v[42:45], v[176:179], v[228:231], v[42:45]
	v_mfma_f32_16x16x32_bf16 v[30:33], v[168:171], v[236:239], v[30:33]
	v_mfma_f32_16x16x32_bf16 v[26:29], v[176:179], v[236:239], v[26:29]
	v_mfma_f32_16x16x32_bf16 v[12:15], v[168:171], v[244:247], v[12:15]
	v_mfma_f32_16x16x32_bf16 v[8:11], v[176:179], v[244:247], v[8:11]
	v_mfma_f32_16x16x32_bf16 v[54:57], v[180:183], v[216:219], v[54:57]
	v_mfma_f32_16x16x32_bf16 v[50:53], v[208:211], v[216:219], v[50:53]
	v_mfma_f32_16x16x32_bf16 v[38:41], v[180:183], v[224:227], v[38:41]
	v_mfma_f32_16x16x32_bf16 v[34:37], v[208:211], v[224:227], v[34:37]
	v_mfma_f32_16x16x32_bf16 v[22:25], v[180:183], v[232:235], v[22:25]
	v_mfma_f32_16x16x32_bf16 v[16:19], v[208:211], v[232:235], v[16:19]
	v_mfma_f32_16x16x32_bf16 v[4:7], v[180:183], v[240:243], v[4:7]
	v_mfma_f32_16x16x32_bf16 v[0:3], v[208:211], v[240:243], v[0:3]
	v_mfma_f32_16x16x32_bf16 v[54:57], v[184:187], v[220:223], v[54:57]
	v_mfma_f32_16x16x32_bf16 v[50:53], v[212:215], v[220:223], v[50:53]
	v_mfma_f32_16x16x32_bf16 v[38:41], v[184:187], v[228:231], v[38:41]
	v_mfma_f32_16x16x32_bf16 v[34:37], v[212:215], v[228:231], v[34:37]
	v_mfma_f32_16x16x32_bf16 v[22:25], v[184:187], v[236:239], v[22:25]
	v_mfma_f32_16x16x32_bf16 v[16:19], v[212:215], v[236:239], v[16:19]
	v_mfma_f32_16x16x32_bf16 v[4:7], v[184:187], v[244:247], v[4:7]
	v_mfma_f32_16x16x32_bf16 v[0:3], v[212:215], v[244:247], v[0:3]
	s_barrier
	s_add_i32 s16, 0, 0x18000
	v_add_u32_e32 v154, s16, v163
	s_add_i32 s17, 0, 0x1c000
	ds_read_b128 v[144:147], v154
	ds_read_b128 v[168:171], v154 offset:1024
	ds_read_b128 v[172:175], v154 offset:2048
	ds_read_b128 v[176:179], v154 offset:3072
	v_add_u32_e32 v154, s17, v163
	ds_read_b128 v[180:183], v154
	ds_read_b128 v[184:187], v154 offset:1024
	ds_read_b128 v[208:211], v154 offset:2048
	ds_read_b128 v[212:215], v154 offset:3072
	s_add_u32 s14, s44, 0xb0000
	s_addc_u32 s15, s45, 0
	s_mov_b32 m0, s33
	v_lshl_add_u64 v[156:157], s[14:15], 0, v[130:131]
	ds_read_b128 v[216:219], v166 offset:32768
	ds_read_b128 v[220:223], v166 offset:33792
	ds_read_b128 v[224:227], v166 offset:34816
	ds_read_b128 v[228:231], v166 offset:35840
	ds_read_b128 v[232:235], v166 offset:36864
	ds_read_b128 v[236:239], v166 offset:37888
	ds_read_b128 v[240:243], v166 offset:38912
	ds_read_b128 v[244:247], v166 offset:39936
	global_load_lds_dwordx4 v[156:157], off
	v_lshl_add_u64 v[156:157], s[14:15], 0, v[134:135]
	s_mov_b32 m0, s46
	s_nop 0
	global_load_lds_dwordx4 v[156:157], off
	s_waitcnt vmcnt(8)
	s_waitcnt lgkmcnt(0)
	s_barrier
	s_waitcnt lgkmcnt(0)
	v_mfma_f32_16x16x32_bf16 v[126:129], v[144:147], v[216:219], v[126:129]
	v_mfma_f32_16x16x32_bf16 v[122:125], v[172:175], v[216:219], v[122:125]
	v_mfma_f32_16x16x32_bf16 v[110:113], v[144:147], v[224:227], v[110:113]
	v_mfma_f32_16x16x32_bf16 v[106:109], v[172:175], v[224:227], v[106:109]
	v_mfma_f32_16x16x32_bf16 v[94:97], v[144:147], v[232:235], v[94:97]
	v_mfma_f32_16x16x32_bf16 v[90:93], v[172:175], v[232:235], v[90:93]
	v_mfma_f32_16x16x32_bf16 v[78:81], v[144:147], v[240:243], v[78:81]
	v_mfma_f32_16x16x32_bf16 v[74:77], v[172:175], v[240:243], v[74:77]
	v_mfma_f32_16x16x32_bf16 v[126:129], v[168:171], v[220:223], v[126:129]
	v_mfma_f32_16x16x32_bf16 v[122:125], v[176:179], v[220:223], v[122:125]
	v_mfma_f32_16x16x32_bf16 v[110:113], v[168:171], v[228:231], v[110:113]
	v_mfma_f32_16x16x32_bf16 v[106:109], v[176:179], v[228:231], v[106:109]
	v_mfma_f32_16x16x32_bf16 v[94:97], v[168:171], v[236:239], v[94:97]
	v_mfma_f32_16x16x32_bf16 v[90:93], v[176:179], v[236:239], v[90:93]
	v_mfma_f32_16x16x32_bf16 v[78:81], v[168:171], v[244:247], v[78:81]
	v_mfma_f32_16x16x32_bf16 v[74:77], v[176:179], v[244:247], v[74:77]
	v_mfma_f32_16x16x32_bf16 v[118:121], v[180:183], v[216:219], v[118:121]
	v_mfma_f32_16x16x32_bf16 v[114:117], v[208:211], v[216:219], v[114:117]
	v_mfma_f32_16x16x32_bf16 v[102:105], v[180:183], v[224:227], v[102:105]
	v_mfma_f32_16x16x32_bf16 v[98:101], v[208:211], v[224:227], v[98:101]
	v_mfma_f32_16x16x32_bf16 v[86:89], v[180:183], v[232:235], v[86:89]
	v_mfma_f32_16x16x32_bf16 v[82:85], v[208:211], v[232:235], v[82:85]
	v_mfma_f32_16x16x32_bf16 v[70:73], v[180:183], v[240:243], v[70:73]
	v_mfma_f32_16x16x32_bf16 v[66:69], v[208:211], v[240:243], v[66:69]
	v_mfma_f32_16x16x32_bf16 v[118:121], v[184:187], v[220:223], v[118:121]
	v_mfma_f32_16x16x32_bf16 v[114:117], v[212:215], v[220:223], v[114:117]
	v_mfma_f32_16x16x32_bf16 v[102:105], v[184:187], v[228:231], v[102:105]
	v_mfma_f32_16x16x32_bf16 v[98:101], v[212:215], v[228:231], v[98:101]
	v_mfma_f32_16x16x32_bf16 v[86:89], v[184:187], v[236:239], v[86:89]
	v_mfma_f32_16x16x32_bf16 v[82:85], v[212:215], v[236:239], v[82:85]
	v_mfma_f32_16x16x32_bf16 v[70:73], v[184:187], v[244:247], v[70:73]
	v_mfma_f32_16x16x32_bf16 v[66:69], v[212:215], v[244:247], v[66:69]
	s_barrier
	s_add_i32 s14, s16, s28
	v_lshl_add_u64 v[156:157], v[188:189], 0, s[34:35]
	s_mov_b32 m0, s14
	ds_read_b128 v[216:219], v166 offset:49152
	ds_read_b128 v[220:223], v166 offset:50176
	ds_read_b128 v[224:227], v166 offset:51200
	ds_read_b128 v[228:231], v166 offset:52224
	ds_read_b128 v[232:235], v166 offset:53248
	ds_read_b128 v[236:239], v166 offset:54272
	ds_read_b128 v[240:243], v166 offset:55296
	ds_read_b128 v[244:247], v166 offset:56320
	global_load_lds_dwordx4 v[156:157], off
	s_add_i32 m0, s14, 0x2000
	s_add_u32 s14, s42, 0xb0080
	v_lshl_add_u64 v[156:157], v[248:249], 0, s[34:35]
	s_addc_u32 s15, s43, 0
	s_add_i32 s16, s17, s28
	global_load_lds_dwordx4 v[156:157], off
	v_lshl_add_u64 v[156:157], s[14:15], 0, v[132:133]
	s_mov_b32 m0, s16
	s_nop 0
	global_load_lds_dwordx4 v[156:157], off
	v_lshl_add_u64 v[156:157], s[14:15], 0, v[136:137]
	s_add_i32 m0, s16, 0x2000
	s_nop 0
	global_load_lds_dwordx4 v[156:157], off
	v_lshl_add_u64 v[156:157], v[250:251], 0, s[34:35]
	s_mov_b32 m0, s48
	s_nop 0
	global_load_lds_dwordx4 v[156:157], off
	v_lshl_add_u64 v[156:157], v[252:253], 0, s[34:35]
	s_mov_b32 m0, s49
	s_nop 0
	global_load_lds_dwordx4 v[156:157], off
	s_waitcnt vmcnt(8)
	s_waitcnt lgkmcnt(0)
	s_barrier
	s_waitcnt lgkmcnt(0)
	v_mfma_f32_16x16x32_bf16 v[62:65], v[144:147], v[216:219], v[62:65]
	v_mfma_f32_16x16x32_bf16 v[58:61], v[172:175], v[216:219], v[58:61]
	v_mfma_f32_16x16x32_bf16 v[46:49], v[144:147], v[224:227], v[46:49]
	v_mfma_f32_16x16x32_bf16 v[42:45], v[172:175], v[224:227], v[42:45]
	v_mfma_f32_16x16x32_bf16 v[30:33], v[144:147], v[232:235], v[30:33]
	v_mfma_f32_16x16x32_bf16 v[26:29], v[172:175], v[232:235], v[26:29]
	v_mfma_f32_16x16x32_bf16 v[12:15], v[144:147], v[240:243], v[12:15]
	v_mfma_f32_16x16x32_bf16 v[8:11], v[172:175], v[240:243], v[8:11]
	v_mfma_f32_16x16x32_bf16 v[62:65], v[168:171], v[220:223], v[62:65]
	v_mfma_f32_16x16x32_bf16 v[58:61], v[176:179], v[220:223], v[58:61]
	v_mfma_f32_16x16x32_bf16 v[46:49], v[168:171], v[228:231], v[46:49]
	v_mfma_f32_16x16x32_bf16 v[42:45], v[176:179], v[228:231], v[42:45]
	v_mfma_f32_16x16x32_bf16 v[30:33], v[168:171], v[236:239], v[30:33]
	v_mfma_f32_16x16x32_bf16 v[26:29], v[176:179], v[236:239], v[26:29]
	v_mfma_f32_16x16x32_bf16 v[12:15], v[168:171], v[244:247], v[12:15]
	v_mfma_f32_16x16x32_bf16 v[8:11], v[176:179], v[244:247], v[8:11]
	v_mfma_f32_16x16x32_bf16 v[54:57], v[180:183], v[216:219], v[54:57]
	v_mfma_f32_16x16x32_bf16 v[50:53], v[208:211], v[216:219], v[50:53]
	v_mfma_f32_16x16x32_bf16 v[38:41], v[180:183], v[224:227], v[38:41]
	v_mfma_f32_16x16x32_bf16 v[34:37], v[208:211], v[224:227], v[34:37]
	v_mfma_f32_16x16x32_bf16 v[22:25], v[180:183], v[232:235], v[22:25]
	v_mfma_f32_16x16x32_bf16 v[16:19], v[208:211], v[232:235], v[16:19]
	v_mfma_f32_16x16x32_bf16 v[4:7], v[180:183], v[240:243], v[4:7]
	v_mfma_f32_16x16x32_bf16 v[0:3], v[208:211], v[240:243], v[0:3]
	v_mfma_f32_16x16x32_bf16 v[54:57], v[184:187], v[220:223], v[54:57]
	v_mfma_f32_16x16x32_bf16 v[50:53], v[212:215], v[220:223], v[50:53]
	v_mfma_f32_16x16x32_bf16 v[38:41], v[184:187], v[228:231], v[38:41]
	v_mfma_f32_16x16x32_bf16 v[34:37], v[212:215], v[228:231], v[34:37]
	v_mfma_f32_16x16x32_bf16 v[22:25], v[184:187], v[236:239], v[22:25]
	v_mfma_f32_16x16x32_bf16 v[16:19], v[212:215], v[236:239], v[16:19]
	v_mfma_f32_16x16x32_bf16 v[4:7], v[184:187], v[244:247], v[4:7]
	v_mfma_f32_16x16x32_bf16 v[0:3], v[212:215], v[244:247], v[0:3]
	s_barrier
	s_add_i32 s58, s58, 2
	s_add_u32 s56, s56, 0x100
	s_addc_u32 s57, s57, 0
	s_cmp_gt_u32 s58, 41
	s_mov_b64 s[14:15], s[26:27]
	s_cbranch_scc0 .LBB0_2066
	s_setprio 0
	s_and_b64 vcc, exec, s[8:9]
	s_cbranch_vccz .LBB0_2069
	s_barrier
